# in-register proj epilogue (q/k/gate tiles) + per-block K-tile rotation in both projection GEMMs
# speedup vs baseline: 1.0273x; 1.0273x over previous
.LBB0_129:
	s_lshl_b32 s0, s68, 3
	s_and_b32 s16, s0, 56
	s_bfe_u32 s0, s68, 0x30003
	s_or_b32 s24, s16, s0
	s_lshl_b32 s38, s68, 2
	s_lshr_b32 s25, s68, 3
	s_and_b32 s50, s38, 0xffffff00
	s_lshl_b32 s0, s24, 19
	s_add_u32 s4, s41, s0
	s_addc_u32 s5, s49, 0
	s_ashr_i32 s51, s50, 31
	s_lshl_b64 s[0:1], s[50:51], 11
	s_add_u32 s26, s21, s0
	v_readfirstlane_b32 s0, v144
	s_addc_u32 s27, s33, s1
	s_ashr_i32 s28, s0, 6
	s_lshl_b32 s0, s28, 5
	s_ashr_i32 s1, s0, 31
	s_lshl_b64 s[0:1], s[0:1], 11
	s_add_u32 s4, s4, s0
	s_addc_u32 s5, s5, s1
	s_add_u32 s0, s26, s0
	s_addc_u32 s1, s27, s1
	s_lshl_b32 s26, s28, 12
	s_add_i32 s27, s26, 0x8000
	s_and_b32 s81, s24, 7
	s_lshl_b32 s81, s81, 8
	s_add_u32 s4, s4, s81
	s_addc_u32 s5, s5, 0
	s_add_u32 s0, s0, s81
	s_addc_u32 s1, s1, 0
	s_add_u32 s28, s4, 0x4000
	s_barrier
	s_mov_b32 m0, s26
	global_load_lds_dwordx4 v145, s[4:5]
	s_addc_u32 s29, s5, 0
	s_or_b32 s30, s26, 0x400
	s_mov_b32 m0, s30
	global_load_lds_dwordx4 v185, s[28:29]
	s_add_u32 s28, s4, 0x8000
	s_addc_u32 s29, s5, 0
	s_or_b32 s30, s26, 0x800
	s_mov_b32 m0, s30
	global_load_lds_dwordx4 v145, s[28:29]
	s_add_u32 s28, s4, 0xc000
	s_addc_u32 s29, s5, 0
	s_or_b32 s30, s26, 0xc00
	s_mov_b32 m0, s30
	global_load_lds_dwordx4 v185, s[28:29]
	s_add_u32 s28, s0, 0x4000
	s_mov_b32 m0, s27
	global_load_lds_dwordx4 v145, s[0:1]
	s_addc_u32 s29, s1, 0
	s_add_i32 s27, s26, 0x8400
	s_mov_b32 m0, s27
	global_load_lds_dwordx4 v185, s[28:29]
	s_add_u32 s28, s0, 0x8000
	s_addc_u32 s29, s1, 0
	s_add_i32 s27, s26, 0x8800
	s_mov_b32 m0, s27
	global_load_lds_dwordx4 v145, s[28:29]
	s_add_u32 s28, s0, 0xc000
	s_addc_u32 s29, s1, 0
	s_add_i32 s27, s26, 0x8c00
	s_mov_b32 m0, s27
	global_load_lds_dwordx4 v185, s[28:29]
	s_sub_u32 s4, s4, s81
	s_subb_u32 s5, s5, 0
	s_sub_u32 s0, s0, s81
	s_subb_u32 s1, s1, 0
	s_add_u32 s27, s0, 0xc000
	s_addc_u32 s28, s1, 0
	s_add_u32 s29, s0, 0x8000
	s_addc_u32 s30, s1, 0
	s_add_u32 s31, s0, 0x4000
	s_addc_u32 s34, s1, 0
	s_add_u32 s35, s0, 0x0
	s_addc_u32 s36, s1, 0
	s_add_u32 s37, s4, 0xc000
	s_addc_u32 s39, s5, 0
	s_add_u32 s40, s4, 0x8000
	s_addc_u32 s42, s5, 0
	s_add_u32 s43, s4, 0x4000
	s_addc_u32 s44, s5, 0
	s_add_u32 s45, s4, 0x0
	s_addc_u32 s46, s5, 0
	s_mov_b64 s[0:1], 0
	s_mov_b32 s48, s17
	s_mov_b32 s47, s17
	v_mov_b32_e32 v0, v147
	v_mov_b32_e32 v1, v147
	v_mov_b32_e32 v2, v147
	v_mov_b32_e32 v3, v147
	v_mov_b32_e32 v4, v147
	v_mov_b32_e32 v5, v147
	v_mov_b32_e32 v6, v147
	v_mov_b32_e32 v7, v147
	v_mov_b32_e32 v8, v147
	v_mov_b32_e32 v9, v147
	v_mov_b32_e32 v10, v147
	v_mov_b32_e32 v11, v147
	v_mov_b32_e32 v12, v147
	v_mov_b32_e32 v13, v147
	v_mov_b32_e32 v14, v147
	v_mov_b32_e32 v15, v147
	v_mov_b32_e32 v16, v147
	v_mov_b32_e32 v17, v147
	v_mov_b32_e32 v18, v147
	v_mov_b32_e32 v19, v147
	v_mov_b32_e32 v20, v147
	v_mov_b32_e32 v21, v147
	v_mov_b32_e32 v22, v147
	v_mov_b32_e32 v23, v147
	v_mov_b32_e32 v24, v147
	v_mov_b32_e32 v25, v147
	v_mov_b32_e32 v26, v147
	v_mov_b32_e32 v27, v147
	v_mov_b32_e32 v28, v147
	v_mov_b32_e32 v29, v147
	v_mov_b32_e32 v30, v147
	v_mov_b32_e32 v31, v147
	v_mov_b32_e32 v32, v147
	v_mov_b32_e32 v33, v147
	v_mov_b32_e32 v34, v147
	v_mov_b32_e32 v35, v147
	v_mov_b32_e32 v36, v147
	v_mov_b32_e32 v37, v147
	v_mov_b32_e32 v38, v147
	v_mov_b32_e32 v39, v147
	v_mov_b32_e32 v40, v147
	v_mov_b32_e32 v41, v147
	v_mov_b32_e32 v42, v147
	v_mov_b32_e32 v43, v147
	v_mov_b32_e32 v44, v147
	v_mov_b32_e32 v45, v147
	v_mov_b32_e32 v46, v147
	v_mov_b32_e32 v47, v147
	v_mov_b32_e32 v48, v147
	v_mov_b32_e32 v49, v147
	v_mov_b32_e32 v50, v147
	v_mov_b32_e32 v51, v147
	v_mov_b32_e32 v52, v147
	v_mov_b32_e32 v53, v147
	v_mov_b32_e32 v54, v147
	v_mov_b32_e32 v55, v147
	v_mov_b32_e32 v56, v147
	v_mov_b32_e32 v57, v147
	v_mov_b32_e32 v58, v147
	v_mov_b32_e32 v59, v147
	v_mov_b32_e32 v60, v147
	v_mov_b32_e32 v61, v147
	v_mov_b32_e32 v62, v147
	v_mov_b32_e32 v63, v147
	v_mov_b32_e32 v64, v147
	v_mov_b32_e32 v65, v147
	v_mov_b32_e32 v66, v147
	v_mov_b32_e32 v67, v147
	v_mov_b32_e32 v68, v147
	v_mov_b32_e32 v69, v147
	v_mov_b32_e32 v70, v147
	v_mov_b32_e32 v71, v147
	v_mov_b32_e32 v72, v147
	v_mov_b32_e32 v73, v147
	v_mov_b32_e32 v74, v147
	v_mov_b32_e32 v75, v147
	v_mov_b32_e32 v76, v147
	v_mov_b32_e32 v77, v147
	v_mov_b32_e32 v78, v147
	v_mov_b32_e32 v79, v147
	v_mov_b32_e32 v80, v147
	v_mov_b32_e32 v81, v147
	v_mov_b32_e32 v82, v147
	v_mov_b32_e32 v83, v147
	v_mov_b32_e32 v84, v147
	v_mov_b32_e32 v85, v147
	v_mov_b32_e32 v86, v147
	v_mov_b32_e32 v87, v147
	v_mov_b32_e32 v88, v147
	v_mov_b32_e32 v89, v147
	v_mov_b32_e32 v90, v147
	v_mov_b32_e32 v91, v147
	v_mov_b32_e32 v92, v147
	v_mov_b32_e32 v93, v147
	v_mov_b32_e32 v94, v147
	v_mov_b32_e32 v95, v147
	v_mov_b32_e32 v96, v147
	v_mov_b32_e32 v97, v147
	v_mov_b32_e32 v98, v147
	v_mov_b32_e32 v99, v147
	v_mov_b32_e32 v100, v147
	v_mov_b32_e32 v101, v147
	v_mov_b32_e32 v102, v147
	v_mov_b32_e32 v103, v147
	v_mov_b32_e32 v104, v147
	v_mov_b32_e32 v105, v147
	v_mov_b32_e32 v106, v147
	v_mov_b32_e32 v107, v147
	v_mov_b32_e32 v108, v147
	v_mov_b32_e32 v109, v147
	v_mov_b32_e32 v110, v147
	v_mov_b32_e32 v111, v147
	v_mov_b32_e32 v112, v147
	v_mov_b32_e32 v113, v147
	v_mov_b32_e32 v114, v147
	v_mov_b32_e32 v115, v147
	v_mov_b32_e32 v116, v147
	v_mov_b32_e32 v117, v147
	v_mov_b32_e32 v118, v147
	v_mov_b32_e32 v119, v147
	v_mov_b32_e32 v120, v147
	v_mov_b32_e32 v121, v147
	v_mov_b32_e32 v122, v147
	v_mov_b32_e32 v123, v147
	v_mov_b32_e32 v124, v147
	v_mov_b32_e32 v125, v147
	v_mov_b32_e32 v126, v147
	v_mov_b32_e32 v127, v147
	s_branch .LBB0_131

.LBB0_133:
	s_andn2_b64 vcc, exec, s[4:5]
	s_cbranch_vccnz .LBB0_130
	s_add_i32 s52, s48, 0x10000
	s_and_b32 s4, s52, 0x10000
	s_add_i32 s53, s4, s26
	s_add_i32 s54, s53, 0x8000
	s_add_u32 s82, s0, s81
	s_addk_i32 s82, 0x80
	s_and_b32 s82, s82, 0x7ff
	s_mov_b32 s83, 0
	s_add_u32 s4, s45, s82
	s_addc_u32 s5, s46, s83
	s_mov_b32 m0, s53
	global_load_lds_dwordx4 v145, s[4:5]
	s_add_u32 s4, s43, s82
	s_addc_u32 s5, s44, s83
	s_add_i32 s55, s53, 0x400
	s_mov_b32 m0, s55
	global_load_lds_dwordx4 v185, s[4:5]
	s_add_u32 s4, s40, s82
	s_addc_u32 s5, s42, s83
	s_add_i32 s55, s53, 0x800
	s_mov_b32 m0, s55
	global_load_lds_dwordx4 v145, s[4:5]
	s_add_u32 s4, s37, s82
	s_addc_u32 s5, s39, s83
	s_add_i32 s55, s53, 0xc00
	s_mov_b32 m0, s55
	global_load_lds_dwordx4 v185, s[4:5]
	s_add_u32 s4, s35, s82
	s_addc_u32 s5, s36, s83
	s_mov_b32 m0, s54
	global_load_lds_dwordx4 v145, s[4:5]
	s_add_u32 s4, s31, s82
	s_addc_u32 s5, s34, s83
	s_add_i32 s54, s53, 0x8400
	s_mov_b32 m0, s54
	global_load_lds_dwordx4 v185, s[4:5]
	s_add_u32 s4, s29, s82
	s_addc_u32 s5, s30, s83
	s_add_i32 s54, s53, 0x8800
	s_mov_b32 m0, s54
	global_load_lds_dwordx4 v145, s[4:5]
	s_add_u32 s4, s27, s82
	s_addc_u32 s5, s28, s83
	s_add_i32 s53, s53, 0x8c00
	s_mov_b32 m0, s53
	global_load_lds_dwordx4 v185, s[4:5]
	s_branch .LBB0_130
.LBB0_135:
	s_lshr_b32 s0, s68, 6
	s_sub_u32 s0, s0, 4
	s_cmp_lt_u32 s0, 2
	s_cbranch_scc1 .Lpe_old_L0
	s_cmp_eq_u32 s0, 4
	s_cbranch_scc1 .Lpe_old_L0
	s_mov_b32 s98, 0
	s_mov_b32 s99, s68
.Lpe_entry_L0:
	s_nop 7
	s_and_b32 s24, s99, 7
	s_lshl_b32 s24, s24, 3
	s_bfe_u32 s25, s99, 0x30003
	s_or_b32 s24, s24, s25
	s_lshr_b32 s25, s99, 6
	v_readfirstlane_b32 s26, v178
	v_readlane_b32 s72, v254, 0
	v_readlane_b32 s73, v254, 1
	s_lshr_b32 s26, s26, 6
	s_lshr_b32 s27, s26, 2
	s_and_b32 s28, s26, 3
	s_lshl_b32 s29, s24, 8
	s_lshl_b32 s30, s27, 7
	s_add_u32 s29, s29, s30
	s_lshl_b32 s30, s25, 8
	s_lshl_b32 s31, s28, 6
	s_add_u32 s30, s30, s31
	s_lshl_b32 s31, s29, 5
	s_add_u32 s94, s72, 0x1ad20000
	s_addc_u32 s95, s73, 0
	s_add_u32 s94, s94, s31
	s_addc_u32 s95, s95, 0
	v_and_b32_e32 v197, 31, v179
	v_lshrrev_b32_e32 v146, 5, v179
	v_lshlrev_b32_e32 v180, 5, v197
	v_lshlrev_b32_e32 v146, 4, v146
	global_load_dwordx4 v[128:131], v180, s[94:95] offset:0
	global_load_dwordx4 v[132:135], v180, s[94:95] offset:16
	global_load_dwordx4 v[136:139], v180, s[94:95] offset:1024
	global_load_dwordx4 v[140:143], v180, s[94:95] offset:1040
	global_load_dwordx4 v[164:167], v180, s[94:95] offset:2048
	global_load_dwordx4 v[168:171], v180, s[94:95] offset:2064
	global_load_dwordx4 v[246:249], v180, s[94:95] offset:3072
	global_load_dwordx4 v[250:253], v180, s[94:95] offset:3088
	s_mul_i32 s31, s29, 0x2200
	s_lshl_b32 s32, s30, 1
	s_add_u32 s31, s31, s32
	s_add_u32 s74, s72, 0xc120000
	s_addc_u32 s75, s73, 0
	s_add_u32 s74, s74, s31
	s_addc_u32 s75, s75, 0
	v_mul_u32_u24_e32 v181, 0x2200, v197
	v_add_u32_e32 v181, v181, v146
	s_cmp_ge_u32 s25, 9
	s_cbranch_scc1 .Lpe_gates_L0
	s_lshr_b32 s34, s25, 1
	s_cmp_ge_u32 s25, 6
	s_cselect_b32 s35, 1, 0
	s_sub_u32 s34, s34, s35
	s_lshl_b32 s35, s98, 2
	s_add_u32 s35, s35, s34
	s_lshl_b32 s35, s35, 8
	v_readlane_b32 s82, v254, 14
	v_readlane_b32 s83, v254, 15
	s_add_u32 s82, s82, s35
	s_addc_u32 s83, s83, 0
	global_load_dwordx4 v[198:201], v146, s[82:83] offset:0
	global_load_dwordx4 v[202:205], v146, s[82:83] offset:32
	global_load_dwordx4 v[206:209], v146, s[82:83] offset:64
	global_load_dwordx4 v[210:213], v146, s[82:83] offset:96
	global_load_dwordx4 v[214:217], v146, s[82:83] offset:128
	global_load_dwordx4 v[218:221], v146, s[82:83] offset:160
	global_load_dwordx4 v[222:225], v146, s[82:83] offset:192
	global_load_dwordx4 v[226:229], v146, s[82:83] offset:224
	s_and_b32 s35, s34, 1
	s_cmp_eq_u32 s35, 0
	s_cselect_b32 s36, 0x3e000000, 1.0
	s_and_b32 s35, s29, 0x7ff
	s_lshl_b32 s35, s35, 7
	s_add_u32 s96, s72, 0x1ada0000
	s_addc_u32 s97, s73, 0
	s_add_u32 s96, s96, s35
	s_addc_u32 s97, s97, 0
	s_add_u32 s100, s96, 0x40000
	s_addc_u32 s101, s97, 0
	s_cmp_ge_u32 s34, 2
	s_cselect_b32 s37, 1, 0
	s_waitcnt vmcnt(8)
	v_lshlrev_b32_e32 v180, 7, v197
	v_add_u32_e32 v180, v180, v146
	v_mov_b32_e32 v197, 0x358637bd
	v_pk_add_f32 v[128:129], v[128:129], v[130:131]
	v_pk_add_f32 v[132:133], v[132:133], v[134:135]
	v_pk_add_f32 v[136:137], v[136:137], v[138:139]
	v_pk_add_f32 v[140:141], v[140:141], v[142:143]
	v_pk_add_f32 v[164:165], v[164:165], v[166:167]
	v_pk_add_f32 v[168:169], v[168:169], v[170:171]
	v_pk_add_f32 v[246:247], v[246:247], v[248:249]
	v_pk_add_f32 v[250:251], v[250:251], v[252:253]
	v_pk_add_f32 v[128:129], v[128:129], v[132:133]
	v_pk_add_f32 v[136:137], v[136:137], v[140:141]
	v_pk_add_f32 v[164:165], v[164:165], v[168:169]
	v_pk_add_f32 v[246:247], v[246:247], v[250:251]
	v_add_f32_e32 v128, v128, v129
	v_add_f32_e32 v136, v136, v137
	v_add_f32_e32 v164, v164, v165
	v_add_f32_e32 v246, v246, v247
	v_fmamk_f32 v128, v128, 0x3a800000, v197
	v_fmamk_f32 v136, v136, 0x3a800000, v197
	v_fmamk_f32 v164, v164, 0x3a800000, v197
	v_fmamk_f32 v246, v246, 0x3a800000, v197
	v_rsq_f32_e32 v172, v128
	v_rsq_f32_e32 v173, v136
	v_rsq_f32_e32 v174, v164
	v_rsq_f32_e32 v175, v246
	s_nop 0
	s_cmp_eq_u32 s37, 0
	s_cbranch_scc1 .Lpe_norope_ld_L0
	global_load_dwordx4 v[230:233], v180, s[96:97] offset:0
	global_load_dwordx4 v[234:237], v180, s[96:97] offset:32
	global_load_dwordx4 v[238:241], v180, s[96:97] offset:64
	global_load_dwordx4 v[242:245], v180, s[96:97] offset:96
	global_load_dwordx4 v[148:151], v180, s[100:101] offset:0
	global_load_dwordx4 v[152:155], v180, s[100:101] offset:32
	global_load_dwordx4 v[156:159], v180, s[100:101] offset:64
	global_load_dwordx4 v[160:163], v180, s[100:101] offset:96
.Lpe_norope_ld_L0:
	v_pk_mul_f32 v[128:129], v[0:1], v[0:1]
	v_pk_mul_f32 v[130:131], v[16:17], v[16:17]
	v_pk_mul_f32 v[132:133], v[32:33], v[32:33]
	v_pk_mul_f32 v[134:135], v[48:49], v[48:49]
	v_pk_mul_f32 v[136:137], v[64:65], v[64:65]
	v_pk_mul_f32 v[138:139], v[80:81], v[80:81]
	v_pk_mul_f32 v[140:141], v[96:97], v[96:97]
	v_pk_mul_f32 v[142:143], v[112:113], v[112:113]
	v_pk_fma_f32 v[128:129], v[2:3], v[2:3], v[128:129]
	v_pk_fma_f32 v[130:131], v[18:19], v[18:19], v[130:131]
	v_pk_fma_f32 v[132:133], v[34:35], v[34:35], v[132:133]
	v_pk_fma_f32 v[134:135], v[50:51], v[50:51], v[134:135]
	v_pk_fma_f32 v[136:137], v[66:67], v[66:67], v[136:137]
	v_pk_fma_f32 v[138:139], v[82:83], v[82:83], v[138:139]
	v_pk_fma_f32 v[140:141], v[98:99], v[98:99], v[140:141]
	v_pk_fma_f32 v[142:143], v[114:115], v[114:115], v[142:143]
	v_pk_fma_f32 v[128:129], v[4:5], v[4:5], v[128:129]
	v_pk_fma_f32 v[130:131], v[20:21], v[20:21], v[130:131]
	v_pk_fma_f32 v[132:133], v[36:37], v[36:37], v[132:133]
	v_pk_fma_f32 v[134:135], v[52:53], v[52:53], v[134:135]
	v_pk_fma_f32 v[136:137], v[68:69], v[68:69], v[136:137]
	v_pk_fma_f32 v[138:139], v[84:85], v[84:85], v[138:139]
	v_pk_fma_f32 v[140:141], v[100:101], v[100:101], v[140:141]
	v_pk_fma_f32 v[142:143], v[116:117], v[116:117], v[142:143]
	v_pk_fma_f32 v[128:129], v[6:7], v[6:7], v[128:129]
	v_pk_fma_f32 v[130:131], v[22:23], v[22:23], v[130:131]
	v_pk_fma_f32 v[132:133], v[38:39], v[38:39], v[132:133]
	v_pk_fma_f32 v[134:135], v[54:55], v[54:55], v[134:135]
	v_pk_fma_f32 v[136:137], v[70:71], v[70:71], v[136:137]
	v_pk_fma_f32 v[138:139], v[86:87], v[86:87], v[138:139]
	v_pk_fma_f32 v[140:141], v[102:103], v[102:103], v[140:141]
	v_pk_fma_f32 v[142:143], v[118:119], v[118:119], v[142:143]
	v_pk_fma_f32 v[128:129], v[8:9], v[8:9], v[128:129]
	v_pk_fma_f32 v[130:131], v[24:25], v[24:25], v[130:131]
	v_pk_fma_f32 v[132:133], v[40:41], v[40:41], v[132:133]
	v_pk_fma_f32 v[134:135], v[56:57], v[56:57], v[134:135]
	v_pk_fma_f32 v[136:137], v[72:73], v[72:73], v[136:137]
	v_pk_fma_f32 v[138:139], v[88:89], v[88:89], v[138:139]
	v_pk_fma_f32 v[140:141], v[104:105], v[104:105], v[140:141]
	v_pk_fma_f32 v[142:143], v[120:121], v[120:121], v[142:143]
	v_pk_fma_f32 v[128:129], v[10:11], v[10:11], v[128:129]
	v_pk_fma_f32 v[130:131], v[26:27], v[26:27], v[130:131]
	v_pk_fma_f32 v[132:133], v[42:43], v[42:43], v[132:133]
	v_pk_fma_f32 v[134:135], v[58:59], v[58:59], v[134:135]
	v_pk_fma_f32 v[136:137], v[74:75], v[74:75], v[136:137]
	v_pk_fma_f32 v[138:139], v[90:91], v[90:91], v[138:139]
	v_pk_fma_f32 v[140:141], v[106:107], v[106:107], v[140:141]
	v_pk_fma_f32 v[142:143], v[122:123], v[122:123], v[142:143]
	v_pk_fma_f32 v[128:129], v[12:13], v[12:13], v[128:129]
	v_pk_fma_f32 v[130:131], v[28:29], v[28:29], v[130:131]
	v_pk_fma_f32 v[132:133], v[44:45], v[44:45], v[132:133]
	v_pk_fma_f32 v[134:135], v[60:61], v[60:61], v[134:135]
	v_pk_fma_f32 v[136:137], v[76:77], v[76:77], v[136:137]
	v_pk_fma_f32 v[138:139], v[92:93], v[92:93], v[138:139]
	v_pk_fma_f32 v[140:141], v[108:109], v[108:109], v[140:141]
	v_pk_fma_f32 v[142:143], v[124:125], v[124:125], v[142:143]
	v_pk_fma_f32 v[128:129], v[14:15], v[14:15], v[128:129]
	v_pk_fma_f32 v[130:131], v[30:31], v[30:31], v[130:131]
	v_pk_fma_f32 v[132:133], v[46:47], v[46:47], v[132:133]
	v_pk_fma_f32 v[134:135], v[62:63], v[62:63], v[134:135]
	v_pk_fma_f32 v[136:137], v[78:79], v[78:79], v[136:137]
	v_pk_fma_f32 v[138:139], v[94:95], v[94:95], v[138:139]
	v_pk_fma_f32 v[140:141], v[110:111], v[110:111], v[140:141]
	v_pk_fma_f32 v[142:143], v[126:127], v[126:127], v[142:143]
	v_pk_add_f32 v[128:129], v[128:129], v[130:131]
	v_pk_add_f32 v[132:133], v[132:133], v[134:135]
	v_pk_add_f32 v[136:137], v[136:137], v[138:139]
	v_pk_add_f32 v[140:141], v[140:141], v[142:143]
	v_add_f32_e32 v164, v128, v129
	v_add_f32_e32 v165, v132, v133
	v_add_f32_e32 v166, v136, v137
	v_add_f32_e32 v167, v140, v141
	v_mov_b32_e32 v168, v164
	v_mov_b32_e32 v169, v165
	v_mov_b32_e32 v170, v166
	v_mov_b32_e32 v171, v167
	s_nop 1
	v_permlane32_swap_b32_e32 v168, v164
	v_permlane32_swap_b32_e32 v169, v165
	v_permlane32_swap_b32_e32 v170, v166
	v_permlane32_swap_b32_e32 v171, v167
	v_add_f32_e32 v164, v164, v168
	v_add_f32_e32 v165, v165, v169
	v_add_f32_e32 v166, v166, v170
	v_add_f32_e32 v167, v167, v171
	v_mul_f32_e32 v168, v172, v172
	v_mul_f32_e32 v169, v173, v173
	v_mul_f32_e32 v170, v174, v174
	v_mul_f32_e32 v171, v175, v175
	v_mul_f32_e32 v168, v168, v164
	v_mul_f32_e32 v169, v169, v165
	v_mul_f32_e32 v170, v170, v166
	v_mul_f32_e32 v171, v171, v167
	v_fmamk_f32 v168, v168, 0x3c800000, v197
	v_fmamk_f32 v169, v169, 0x3c800000, v197
	v_fmamk_f32 v170, v170, 0x3c800000, v197
	v_fmamk_f32 v171, v171, 0x3c800000, v197
	v_rsq_f32_e32 v168, v168
	v_rsq_f32_e32 v169, v169
	v_rsq_f32_e32 v170, v170
	v_rsq_f32_e32 v171, v171
	s_nop 0
	v_mul_f32_e32 v172, v172, v168
	v_mul_f32_e32 v173, v173, v169
	v_mul_f32_e32 v174, v174, v170
	v_mul_f32_e32 v175, v175, v171
	v_mul_f32_e32 v172, s36, v172
	v_mul_f32_e32 v173, s36, v173
	v_mul_f32_e32 v174, s36, v174
	v_mul_f32_e32 v175, s36, v175
	v_pk_mul_f32 v[0:1], v[0:1], v[172:173] op_sel_hi:[1,0]
	v_pk_mul_f32 v[2:3], v[2:3], v[172:173] op_sel_hi:[1,0]
	v_pk_mul_f32 v[4:5], v[4:5], v[172:173] op_sel_hi:[1,0]
	v_pk_mul_f32 v[6:7], v[6:7], v[172:173] op_sel_hi:[1,0]
	v_pk_mul_f32 v[8:9], v[8:9], v[172:173] op_sel_hi:[1,0]
	v_pk_mul_f32 v[10:11], v[10:11], v[172:173] op_sel_hi:[1,0]
	v_pk_mul_f32 v[12:13], v[12:13], v[172:173] op_sel_hi:[1,0]
	v_pk_mul_f32 v[14:15], v[14:15], v[172:173] op_sel_hi:[1,0]
	v_pk_mul_f32 v[16:17], v[16:17], v[172:173] op_sel_hi:[1,0]
	v_pk_mul_f32 v[18:19], v[18:19], v[172:173] op_sel_hi:[1,0]
	v_pk_mul_f32 v[20:21], v[20:21], v[172:173] op_sel_hi:[1,0]
	v_pk_mul_f32 v[22:23], v[22:23], v[172:173] op_sel_hi:[1,0]
	v_pk_mul_f32 v[24:25], v[24:25], v[172:173] op_sel_hi:[1,0]
	v_pk_mul_f32 v[26:27], v[26:27], v[172:173] op_sel_hi:[1,0]
	v_pk_mul_f32 v[28:29], v[28:29], v[172:173] op_sel_hi:[1,0]
	v_pk_mul_f32 v[30:31], v[30:31], v[172:173] op_sel_hi:[1,0]
	s_cmp_eq_u32 s37, 0
	s_cbranch_scc1 .Lpe_wg_norope_L0
	s_waitcnt vmcnt(8)
	s_branch .Lpe_wg_done_L0

.Lpe_wg_done_L0:
	v_pk_mul_f32 v[0:1], v[0:1], v[198:199]
	v_pk_mul_f32 v[2:3], v[2:3], v[200:201]
	v_pk_mul_f32 v[4:5], v[4:5], v[202:203]
	v_pk_mul_f32 v[6:7], v[6:7], v[204:205]
	v_pk_mul_f32 v[8:9], v[8:9], v[206:207]
	v_pk_mul_f32 v[10:11], v[10:11], v[208:209]
	v_pk_mul_f32 v[12:13], v[12:13], v[210:211]
	v_pk_mul_f32 v[14:15], v[14:15], v[212:213]
	v_pk_mul_f32 v[16:17], v[16:17], v[214:215]
	v_pk_mul_f32 v[18:19], v[18:19], v[216:217]
	v_pk_mul_f32 v[20:21], v[20:21], v[218:219]
	v_pk_mul_f32 v[22:23], v[22:23], v[220:221]
	v_pk_mul_f32 v[24:25], v[24:25], v[222:223]
	v_pk_mul_f32 v[26:27], v[26:27], v[224:225]
	v_pk_mul_f32 v[28:29], v[28:29], v[226:227]
	v_pk_mul_f32 v[30:31], v[30:31], v[228:229]
	s_cmp_eq_u32 s37, 0
	s_cbranch_scc1 .Lpe_norope_0_L0
	s_waitcnt vmcnt(0)
	v_pk_mul_f32 v[128:129], v[16:17], v[148:149]
	v_pk_mul_f32 v[164:165], v[16:17], v[230:231]
	v_pk_mul_f32 v[130:131], v[18:19], v[150:151]
	v_pk_mul_f32 v[166:167], v[18:19], v[232:233]
	v_pk_mul_f32 v[132:133], v[20:21], v[152:153]
	v_pk_mul_f32 v[168:169], v[20:21], v[234:235]
	v_pk_mul_f32 v[134:135], v[22:23], v[154:155]
	v_pk_mul_f32 v[170:171], v[22:23], v[236:237]
	v_pk_mul_f32 v[136:137], v[24:25], v[156:157]
	v_pk_mul_f32 v[246:247], v[24:25], v[238:239]
	v_pk_mul_f32 v[138:139], v[26:27], v[158:159]
	v_pk_mul_f32 v[248:249], v[26:27], v[240:241]
	v_pk_mul_f32 v[140:141], v[28:29], v[160:161]
	v_pk_mul_f32 v[250:251], v[28:29], v[242:243]
	v_pk_mul_f32 v[142:143], v[30:31], v[162:163]
	v_pk_mul_f32 v[252:253], v[30:31], v[244:245]
	v_pk_fma_f32 v[16:17], v[0:1], v[148:149], v[164:165]
	v_pk_fma_f32 v[0:1], v[0:1], v[230:231], v[128:129] neg_lo:[0,0,1] neg_hi:[0,0,1]
	v_pk_fma_f32 v[18:19], v[2:3], v[150:151], v[166:167]
	v_pk_fma_f32 v[2:3], v[2:3], v[232:233], v[130:131] neg_lo:[0,0,1] neg_hi:[0,0,1]
	v_pk_fma_f32 v[20:21], v[4:5], v[152:153], v[168:169]
	v_pk_fma_f32 v[4:5], v[4:5], v[234:235], v[132:133] neg_lo:[0,0,1] neg_hi:[0,0,1]
	v_pk_fma_f32 v[22:23], v[6:7], v[154:155], v[170:171]
	v_pk_fma_f32 v[6:7], v[6:7], v[236:237], v[134:135] neg_lo:[0,0,1] neg_hi:[0,0,1]
	v_pk_fma_f32 v[24:25], v[8:9], v[156:157], v[246:247]
	v_pk_fma_f32 v[8:9], v[8:9], v[238:239], v[136:137] neg_lo:[0,0,1] neg_hi:[0,0,1]
	v_pk_fma_f32 v[26:27], v[10:11], v[158:159], v[248:249]
	v_pk_fma_f32 v[10:11], v[10:11], v[240:241], v[138:139] neg_lo:[0,0,1] neg_hi:[0,0,1]
	v_pk_fma_f32 v[28:29], v[12:13], v[160:161], v[250:251]
	v_pk_fma_f32 v[12:13], v[12:13], v[242:243], v[140:141] neg_lo:[0,0,1] neg_hi:[0,0,1]
	v_pk_fma_f32 v[30:31], v[14:15], v[162:163], v[252:253]
	v_pk_fma_f32 v[14:15], v[14:15], v[244:245], v[142:143] neg_lo:[0,0,1] neg_hi:[0,0,1]
	s_add_u32 s96, s96, 0x1000
	s_addc_u32 s97, s97, 0
	s_add_u32 s100, s100, 0x1000
	s_addc_u32 s101, s101, 0
	global_load_dwordx4 v[230:233], v180, s[96:97] offset:0
	global_load_dwordx4 v[234:237], v180, s[96:97] offset:32
	global_load_dwordx4 v[238:241], v180, s[96:97] offset:64
	global_load_dwordx4 v[242:245], v180, s[96:97] offset:96
	global_load_dwordx4 v[148:151], v180, s[100:101] offset:0
	global_load_dwordx4 v[152:155], v180, s[100:101] offset:32
	global_load_dwordx4 v[156:159], v180, s[100:101] offset:64
	global_load_dwordx4 v[160:163], v180, s[100:101] offset:96
.Lpe_norope_0_L0:
	v_cvt_pk_bf16_f32 v0, v0, v1
	v_cvt_pk_bf16_f32 v1, v2, v3
	v_cvt_pk_bf16_f32 v2, v4, v5
	v_cvt_pk_bf16_f32 v3, v6, v7
	v_cvt_pk_bf16_f32 v4, v8, v9
	v_cvt_pk_bf16_f32 v5, v10, v11
	v_cvt_pk_bf16_f32 v6, v12, v13
	v_cvt_pk_bf16_f32 v7, v14, v15
	v_cvt_pk_bf16_f32 v16, v16, v17
	v_cvt_pk_bf16_f32 v17, v18, v19
	v_cvt_pk_bf16_f32 v18, v20, v21
	v_cvt_pk_bf16_f32 v19, v22, v23
	v_cvt_pk_bf16_f32 v20, v24, v25
	v_cvt_pk_bf16_f32 v21, v26, v27
	v_cvt_pk_bf16_f32 v22, v28, v29
	v_cvt_pk_bf16_f32 v23, v30, v31
	v_permlane32_swap_b32_e32 v0, v2
	v_permlane32_swap_b32_e32 v1, v3
	v_permlane32_swap_b32_e32 v4, v6
	v_permlane32_swap_b32_e32 v5, v7
	v_permlane32_swap_b32_e32 v16, v18
	v_permlane32_swap_b32_e32 v17, v19
	v_permlane32_swap_b32_e32 v20, v22
	v_permlane32_swap_b32_e32 v21, v23
	global_store_dwordx4 v181, v[0:3], s[74:75] offset:0
	global_store_dwordx4 v181, v[4:7], s[74:75] offset:32
	global_store_dwordx4 v181, v[16:19], s[74:75] offset:64
	global_store_dwordx4 v181, v[20:23], s[74:75] offset:96
	s_add_u32 s74, s74, 0x44000
	s_addc_u32 s75, s75, 0
	v_pk_mul_f32 v[32:33], v[32:33], v[172:173] op_sel:[0,1] op_sel_hi:[1,1]
	v_pk_mul_f32 v[34:35], v[34:35], v[172:173] op_sel:[0,1] op_sel_hi:[1,1]
	v_pk_mul_f32 v[36:37], v[36:37], v[172:173] op_sel:[0,1] op_sel_hi:[1,1]
	v_pk_mul_f32 v[38:39], v[38:39], v[172:173] op_sel:[0,1] op_sel_hi:[1,1]
	v_pk_mul_f32 v[40:41], v[40:41], v[172:173] op_sel:[0,1] op_sel_hi:[1,1]
	v_pk_mul_f32 v[42:43], v[42:43], v[172:173] op_sel:[0,1] op_sel_hi:[1,1]
	v_pk_mul_f32 v[44:45], v[44:45], v[172:173] op_sel:[0,1] op_sel_hi:[1,1]
	v_pk_mul_f32 v[46:47], v[46:47], v[172:173] op_sel:[0,1] op_sel_hi:[1,1]
	v_pk_mul_f32 v[48:49], v[48:49], v[172:173] op_sel:[0,1] op_sel_hi:[1,1]
	v_pk_mul_f32 v[50:51], v[50:51], v[172:173] op_sel:[0,1] op_sel_hi:[1,1]
	v_pk_mul_f32 v[52:53], v[52:53], v[172:173] op_sel:[0,1] op_sel_hi:[1,1]
	v_pk_mul_f32 v[54:55], v[54:55], v[172:173] op_sel:[0,1] op_sel_hi:[1,1]
	v_pk_mul_f32 v[56:57], v[56:57], v[172:173] op_sel:[0,1] op_sel_hi:[1,1]
	v_pk_mul_f32 v[58:59], v[58:59], v[172:173] op_sel:[0,1] op_sel_hi:[1,1]
	v_pk_mul_f32 v[60:61], v[60:61], v[172:173] op_sel:[0,1] op_sel_hi:[1,1]
	v_pk_mul_f32 v[62:63], v[62:63], v[172:173] op_sel:[0,1] op_sel_hi:[1,1]
	v_pk_mul_f32 v[32:33], v[32:33], v[198:199]
	v_pk_mul_f32 v[34:35], v[34:35], v[200:201]
	v_pk_mul_f32 v[36:37], v[36:37], v[202:203]
	v_pk_mul_f32 v[38:39], v[38:39], v[204:205]
	v_pk_mul_f32 v[40:41], v[40:41], v[206:207]
	v_pk_mul_f32 v[42:43], v[42:43], v[208:209]
	v_pk_mul_f32 v[44:45], v[44:45], v[210:211]
	v_pk_mul_f32 v[46:47], v[46:47], v[212:213]
	v_pk_mul_f32 v[48:49], v[48:49], v[214:215]
	v_pk_mul_f32 v[50:51], v[50:51], v[216:217]
	v_pk_mul_f32 v[52:53], v[52:53], v[218:219]
	v_pk_mul_f32 v[54:55], v[54:55], v[220:221]
	v_pk_mul_f32 v[56:57], v[56:57], v[222:223]
	v_pk_mul_f32 v[58:59], v[58:59], v[224:225]
	v_pk_mul_f32 v[60:61], v[60:61], v[226:227]
	v_pk_mul_f32 v[62:63], v[62:63], v[228:229]
	s_cmp_eq_u32 s37, 0
	s_cbranch_scc1 .Lpe_norope_1_L0
	s_waitcnt vmcnt(4)
	v_pk_mul_f32 v[128:129], v[48:49], v[148:149]
	v_pk_mul_f32 v[164:165], v[48:49], v[230:231]
	v_pk_mul_f32 v[130:131], v[50:51], v[150:151]
	v_pk_mul_f32 v[166:167], v[50:51], v[232:233]
	v_pk_mul_f32 v[132:133], v[52:53], v[152:153]
	v_pk_mul_f32 v[168:169], v[52:53], v[234:235]
	v_pk_mul_f32 v[134:135], v[54:55], v[154:155]
	v_pk_mul_f32 v[170:171], v[54:55], v[236:237]
	v_pk_mul_f32 v[136:137], v[56:57], v[156:157]
	v_pk_mul_f32 v[246:247], v[56:57], v[238:239]
	v_pk_mul_f32 v[138:139], v[58:59], v[158:159]
	v_pk_mul_f32 v[248:249], v[58:59], v[240:241]
	v_pk_mul_f32 v[140:141], v[60:61], v[160:161]
	v_pk_mul_f32 v[250:251], v[60:61], v[242:243]
	v_pk_mul_f32 v[142:143], v[62:63], v[162:163]
	v_pk_mul_f32 v[252:253], v[62:63], v[244:245]
	v_pk_fma_f32 v[48:49], v[32:33], v[148:149], v[164:165]
	v_pk_fma_f32 v[32:33], v[32:33], v[230:231], v[128:129] neg_lo:[0,0,1] neg_hi:[0,0,1]
	v_pk_fma_f32 v[50:51], v[34:35], v[150:151], v[166:167]
	v_pk_fma_f32 v[34:35], v[34:35], v[232:233], v[130:131] neg_lo:[0,0,1] neg_hi:[0,0,1]
	v_pk_fma_f32 v[52:53], v[36:37], v[152:153], v[168:169]
	v_pk_fma_f32 v[36:37], v[36:37], v[234:235], v[132:133] neg_lo:[0,0,1] neg_hi:[0,0,1]
	v_pk_fma_f32 v[54:55], v[38:39], v[154:155], v[170:171]
	v_pk_fma_f32 v[38:39], v[38:39], v[236:237], v[134:135] neg_lo:[0,0,1] neg_hi:[0,0,1]
	v_pk_fma_f32 v[56:57], v[40:41], v[156:157], v[246:247]
	v_pk_fma_f32 v[40:41], v[40:41], v[238:239], v[136:137] neg_lo:[0,0,1] neg_hi:[0,0,1]
	v_pk_fma_f32 v[58:59], v[42:43], v[158:159], v[248:249]
	v_pk_fma_f32 v[42:43], v[42:43], v[240:241], v[138:139] neg_lo:[0,0,1] neg_hi:[0,0,1]
	v_pk_fma_f32 v[60:61], v[44:45], v[160:161], v[250:251]
	v_pk_fma_f32 v[44:45], v[44:45], v[242:243], v[140:141] neg_lo:[0,0,1] neg_hi:[0,0,1]
	v_pk_fma_f32 v[62:63], v[46:47], v[162:163], v[252:253]
	v_pk_fma_f32 v[46:47], v[46:47], v[244:245], v[142:143] neg_lo:[0,0,1] neg_hi:[0,0,1]
	s_add_u32 s96, s96, 0x1000
	s_addc_u32 s97, s97, 0
	s_add_u32 s100, s100, 0x1000
	s_addc_u32 s101, s101, 0
	global_load_dwordx4 v[230:233], v180, s[96:97] offset:0
	global_load_dwordx4 v[234:237], v180, s[96:97] offset:32
	global_load_dwordx4 v[238:241], v180, s[96:97] offset:64
	global_load_dwordx4 v[242:245], v180, s[96:97] offset:96
	global_load_dwordx4 v[148:151], v180, s[100:101] offset:0
	global_load_dwordx4 v[152:155], v180, s[100:101] offset:32
	global_load_dwordx4 v[156:159], v180, s[100:101] offset:64
	global_load_dwordx4 v[160:163], v180, s[100:101] offset:96
.Lpe_norope_1_L0:
	v_cvt_pk_bf16_f32 v32, v32, v33
	v_cvt_pk_bf16_f32 v33, v34, v35
	v_cvt_pk_bf16_f32 v34, v36, v37
	v_cvt_pk_bf16_f32 v35, v38, v39
	v_cvt_pk_bf16_f32 v36, v40, v41
	v_cvt_pk_bf16_f32 v37, v42, v43
	v_cvt_pk_bf16_f32 v38, v44, v45
	v_cvt_pk_bf16_f32 v39, v46, v47
	v_cvt_pk_bf16_f32 v48, v48, v49
	v_cvt_pk_bf16_f32 v49, v50, v51
	v_cvt_pk_bf16_f32 v50, v52, v53
	v_cvt_pk_bf16_f32 v51, v54, v55
	v_cvt_pk_bf16_f32 v52, v56, v57
	v_cvt_pk_bf16_f32 v53, v58, v59
	v_cvt_pk_bf16_f32 v54, v60, v61
	v_cvt_pk_bf16_f32 v55, v62, v63
	v_permlane32_swap_b32_e32 v32, v34
	v_permlane32_swap_b32_e32 v33, v35
	v_permlane32_swap_b32_e32 v36, v38
	v_permlane32_swap_b32_e32 v37, v39
	v_permlane32_swap_b32_e32 v48, v50
	v_permlane32_swap_b32_e32 v49, v51
	v_permlane32_swap_b32_e32 v52, v54
	v_permlane32_swap_b32_e32 v53, v55
	global_store_dwordx4 v181, v[32:35], s[74:75] offset:0
	global_store_dwordx4 v181, v[36:39], s[74:75] offset:32
	global_store_dwordx4 v181, v[48:51], s[74:75] offset:64
	global_store_dwordx4 v181, v[52:55], s[74:75] offset:96
	s_add_u32 s74, s74, 0x44000
	s_addc_u32 s75, s75, 0
	v_pk_mul_f32 v[64:65], v[64:65], v[174:175] op_sel_hi:[1,0]
	v_pk_mul_f32 v[66:67], v[66:67], v[174:175] op_sel_hi:[1,0]
	v_pk_mul_f32 v[68:69], v[68:69], v[174:175] op_sel_hi:[1,0]
	v_pk_mul_f32 v[70:71], v[70:71], v[174:175] op_sel_hi:[1,0]
	v_pk_mul_f32 v[72:73], v[72:73], v[174:175] op_sel_hi:[1,0]
	v_pk_mul_f32 v[74:75], v[74:75], v[174:175] op_sel_hi:[1,0]
	v_pk_mul_f32 v[76:77], v[76:77], v[174:175] op_sel_hi:[1,0]
	v_pk_mul_f32 v[78:79], v[78:79], v[174:175] op_sel_hi:[1,0]
	v_pk_mul_f32 v[80:81], v[80:81], v[174:175] op_sel_hi:[1,0]
	v_pk_mul_f32 v[82:83], v[82:83], v[174:175] op_sel_hi:[1,0]
	v_pk_mul_f32 v[84:85], v[84:85], v[174:175] op_sel_hi:[1,0]
	v_pk_mul_f32 v[86:87], v[86:87], v[174:175] op_sel_hi:[1,0]
	v_pk_mul_f32 v[88:89], v[88:89], v[174:175] op_sel_hi:[1,0]
	v_pk_mul_f32 v[90:91], v[90:91], v[174:175] op_sel_hi:[1,0]
	v_pk_mul_f32 v[92:93], v[92:93], v[174:175] op_sel_hi:[1,0]
	v_pk_mul_f32 v[94:95], v[94:95], v[174:175] op_sel_hi:[1,0]
	v_pk_mul_f32 v[64:65], v[64:65], v[198:199]
	v_pk_mul_f32 v[66:67], v[66:67], v[200:201]
	v_pk_mul_f32 v[68:69], v[68:69], v[202:203]
	v_pk_mul_f32 v[70:71], v[70:71], v[204:205]
	v_pk_mul_f32 v[72:73], v[72:73], v[206:207]
	v_pk_mul_f32 v[74:75], v[74:75], v[208:209]
	v_pk_mul_f32 v[76:77], v[76:77], v[210:211]
	v_pk_mul_f32 v[78:79], v[78:79], v[212:213]
	v_pk_mul_f32 v[80:81], v[80:81], v[214:215]
	v_pk_mul_f32 v[82:83], v[82:83], v[216:217]
	v_pk_mul_f32 v[84:85], v[84:85], v[218:219]
	v_pk_mul_f32 v[86:87], v[86:87], v[220:221]
	v_pk_mul_f32 v[88:89], v[88:89], v[222:223]
	v_pk_mul_f32 v[90:91], v[90:91], v[224:225]
	v_pk_mul_f32 v[92:93], v[92:93], v[226:227]
	v_pk_mul_f32 v[94:95], v[94:95], v[228:229]
	s_cmp_eq_u32 s37, 0
	s_cbranch_scc1 .Lpe_norope_2_L0
	s_waitcnt vmcnt(4)
	v_pk_mul_f32 v[128:129], v[80:81], v[148:149]
	v_pk_mul_f32 v[164:165], v[80:81], v[230:231]
	v_pk_mul_f32 v[130:131], v[82:83], v[150:151]
	v_pk_mul_f32 v[166:167], v[82:83], v[232:233]
	v_pk_mul_f32 v[132:133], v[84:85], v[152:153]
	v_pk_mul_f32 v[168:169], v[84:85], v[234:235]
	v_pk_mul_f32 v[134:135], v[86:87], v[154:155]
	v_pk_mul_f32 v[170:171], v[86:87], v[236:237]
	v_pk_mul_f32 v[136:137], v[88:89], v[156:157]
	v_pk_mul_f32 v[246:247], v[88:89], v[238:239]
	v_pk_mul_f32 v[138:139], v[90:91], v[158:159]
	v_pk_mul_f32 v[248:249], v[90:91], v[240:241]
	v_pk_mul_f32 v[140:141], v[92:93], v[160:161]
	v_pk_mul_f32 v[250:251], v[92:93], v[242:243]
	v_pk_mul_f32 v[142:143], v[94:95], v[162:163]
	v_pk_mul_f32 v[252:253], v[94:95], v[244:245]
	v_pk_fma_f32 v[80:81], v[64:65], v[148:149], v[164:165]
	v_pk_fma_f32 v[64:65], v[64:65], v[230:231], v[128:129] neg_lo:[0,0,1] neg_hi:[0,0,1]
	v_pk_fma_f32 v[82:83], v[66:67], v[150:151], v[166:167]
	v_pk_fma_f32 v[66:67], v[66:67], v[232:233], v[130:131] neg_lo:[0,0,1] neg_hi:[0,0,1]
	v_pk_fma_f32 v[84:85], v[68:69], v[152:153], v[168:169]
	v_pk_fma_f32 v[68:69], v[68:69], v[234:235], v[132:133] neg_lo:[0,0,1] neg_hi:[0,0,1]
	v_pk_fma_f32 v[86:87], v[70:71], v[154:155], v[170:171]
	v_pk_fma_f32 v[70:71], v[70:71], v[236:237], v[134:135] neg_lo:[0,0,1] neg_hi:[0,0,1]
	v_pk_fma_f32 v[88:89], v[72:73], v[156:157], v[246:247]
	v_pk_fma_f32 v[72:73], v[72:73], v[238:239], v[136:137] neg_lo:[0,0,1] neg_hi:[0,0,1]
	v_pk_fma_f32 v[90:91], v[74:75], v[158:159], v[248:249]
	v_pk_fma_f32 v[74:75], v[74:75], v[240:241], v[138:139] neg_lo:[0,0,1] neg_hi:[0,0,1]
	v_pk_fma_f32 v[92:93], v[76:77], v[160:161], v[250:251]
	v_pk_fma_f32 v[76:77], v[76:77], v[242:243], v[140:141] neg_lo:[0,0,1] neg_hi:[0,0,1]
	v_pk_fma_f32 v[94:95], v[78:79], v[162:163], v[252:253]
	v_pk_fma_f32 v[78:79], v[78:79], v[244:245], v[142:143] neg_lo:[0,0,1] neg_hi:[0,0,1]
	s_add_u32 s96, s96, 0x1000
	s_addc_u32 s97, s97, 0
	s_add_u32 s100, s100, 0x1000
	s_addc_u32 s101, s101, 0
	global_load_dwordx4 v[230:233], v180, s[96:97] offset:0
	global_load_dwordx4 v[234:237], v180, s[96:97] offset:32
	global_load_dwordx4 v[238:241], v180, s[96:97] offset:64
	global_load_dwordx4 v[242:245], v180, s[96:97] offset:96
	global_load_dwordx4 v[148:151], v180, s[100:101] offset:0
	global_load_dwordx4 v[152:155], v180, s[100:101] offset:32
	global_load_dwordx4 v[156:159], v180, s[100:101] offset:64
	global_load_dwordx4 v[160:163], v180, s[100:101] offset:96
.Lpe_norope_2_L0:
	v_cvt_pk_bf16_f32 v64, v64, v65
	v_cvt_pk_bf16_f32 v65, v66, v67
	v_cvt_pk_bf16_f32 v66, v68, v69
	v_cvt_pk_bf16_f32 v67, v70, v71
	v_cvt_pk_bf16_f32 v68, v72, v73
	v_cvt_pk_bf16_f32 v69, v74, v75
	v_cvt_pk_bf16_f32 v70, v76, v77
	v_cvt_pk_bf16_f32 v71, v78, v79
	v_cvt_pk_bf16_f32 v80, v80, v81
	v_cvt_pk_bf16_f32 v81, v82, v83
	v_cvt_pk_bf16_f32 v82, v84, v85
	v_cvt_pk_bf16_f32 v83, v86, v87
	v_cvt_pk_bf16_f32 v84, v88, v89
	v_cvt_pk_bf16_f32 v85, v90, v91
	v_cvt_pk_bf16_f32 v86, v92, v93
	v_cvt_pk_bf16_f32 v87, v94, v95
	v_permlane32_swap_b32_e32 v64, v66
	v_permlane32_swap_b32_e32 v65, v67
	v_permlane32_swap_b32_e32 v68, v70
	v_permlane32_swap_b32_e32 v69, v71
	v_permlane32_swap_b32_e32 v80, v82
	v_permlane32_swap_b32_e32 v81, v83
	v_permlane32_swap_b32_e32 v84, v86
	v_permlane32_swap_b32_e32 v85, v87
	global_store_dwordx4 v181, v[64:67], s[74:75] offset:0
	global_store_dwordx4 v181, v[68:71], s[74:75] offset:32
	global_store_dwordx4 v181, v[80:83], s[74:75] offset:64
	global_store_dwordx4 v181, v[84:87], s[74:75] offset:96
	s_add_u32 s74, s74, 0x44000
	s_addc_u32 s75, s75, 0
	v_pk_mul_f32 v[96:97], v[96:97], v[174:175] op_sel:[0,1] op_sel_hi:[1,1]
	v_pk_mul_f32 v[98:99], v[98:99], v[174:175] op_sel:[0,1] op_sel_hi:[1,1]
	v_pk_mul_f32 v[100:101], v[100:101], v[174:175] op_sel:[0,1] op_sel_hi:[1,1]
	v_pk_mul_f32 v[102:103], v[102:103], v[174:175] op_sel:[0,1] op_sel_hi:[1,1]
	v_pk_mul_f32 v[104:105], v[104:105], v[174:175] op_sel:[0,1] op_sel_hi:[1,1]
	v_pk_mul_f32 v[106:107], v[106:107], v[174:175] op_sel:[0,1] op_sel_hi:[1,1]
	v_pk_mul_f32 v[108:109], v[108:109], v[174:175] op_sel:[0,1] op_sel_hi:[1,1]
	v_pk_mul_f32 v[110:111], v[110:111], v[174:175] op_sel:[0,1] op_sel_hi:[1,1]
	v_pk_mul_f32 v[112:113], v[112:113], v[174:175] op_sel:[0,1] op_sel_hi:[1,1]
	v_pk_mul_f32 v[114:115], v[114:115], v[174:175] op_sel:[0,1] op_sel_hi:[1,1]
	v_pk_mul_f32 v[116:117], v[116:117], v[174:175] op_sel:[0,1] op_sel_hi:[1,1]
	v_pk_mul_f32 v[118:119], v[118:119], v[174:175] op_sel:[0,1] op_sel_hi:[1,1]
	v_pk_mul_f32 v[120:121], v[120:121], v[174:175] op_sel:[0,1] op_sel_hi:[1,1]
	v_pk_mul_f32 v[122:123], v[122:123], v[174:175] op_sel:[0,1] op_sel_hi:[1,1]
	v_pk_mul_f32 v[124:125], v[124:125], v[174:175] op_sel:[0,1] op_sel_hi:[1,1]
	v_pk_mul_f32 v[126:127], v[126:127], v[174:175] op_sel:[0,1] op_sel_hi:[1,1]
	v_pk_mul_f32 v[96:97], v[96:97], v[198:199]
	v_pk_mul_f32 v[98:99], v[98:99], v[200:201]
	v_pk_mul_f32 v[100:101], v[100:101], v[202:203]
	v_pk_mul_f32 v[102:103], v[102:103], v[204:205]
	v_pk_mul_f32 v[104:105], v[104:105], v[206:207]
	v_pk_mul_f32 v[106:107], v[106:107], v[208:209]
	v_pk_mul_f32 v[108:109], v[108:109], v[210:211]
	v_pk_mul_f32 v[110:111], v[110:111], v[212:213]
	v_pk_mul_f32 v[112:113], v[112:113], v[214:215]
	v_pk_mul_f32 v[114:115], v[114:115], v[216:217]
	v_pk_mul_f32 v[116:117], v[116:117], v[218:219]
	v_pk_mul_f32 v[118:119], v[118:119], v[220:221]
	v_pk_mul_f32 v[120:121], v[120:121], v[222:223]
	v_pk_mul_f32 v[122:123], v[122:123], v[224:225]
	v_pk_mul_f32 v[124:125], v[124:125], v[226:227]
	v_pk_mul_f32 v[126:127], v[126:127], v[228:229]
	s_cmp_eq_u32 s37, 0
	s_cbranch_scc1 .Lpe_norope_3_L0
	s_waitcnt vmcnt(4)
	v_pk_mul_f32 v[128:129], v[112:113], v[148:149]
	v_pk_mul_f32 v[164:165], v[112:113], v[230:231]
	v_pk_mul_f32 v[130:131], v[114:115], v[150:151]
	v_pk_mul_f32 v[166:167], v[114:115], v[232:233]
	v_pk_mul_f32 v[132:133], v[116:117], v[152:153]
	v_pk_mul_f32 v[168:169], v[116:117], v[234:235]
	v_pk_mul_f32 v[134:135], v[118:119], v[154:155]
	v_pk_mul_f32 v[170:171], v[118:119], v[236:237]
	v_pk_mul_f32 v[136:137], v[120:121], v[156:157]
	v_pk_mul_f32 v[246:247], v[120:121], v[238:239]
	v_pk_mul_f32 v[138:139], v[122:123], v[158:159]
	v_pk_mul_f32 v[248:249], v[122:123], v[240:241]
	v_pk_mul_f32 v[140:141], v[124:125], v[160:161]
	v_pk_mul_f32 v[250:251], v[124:125], v[242:243]
	v_pk_mul_f32 v[142:143], v[126:127], v[162:163]
	v_pk_mul_f32 v[252:253], v[126:127], v[244:245]
	v_pk_fma_f32 v[112:113], v[96:97], v[148:149], v[164:165]
	v_pk_fma_f32 v[96:97], v[96:97], v[230:231], v[128:129] neg_lo:[0,0,1] neg_hi:[0,0,1]
	v_pk_fma_f32 v[114:115], v[98:99], v[150:151], v[166:167]
	v_pk_fma_f32 v[98:99], v[98:99], v[232:233], v[130:131] neg_lo:[0,0,1] neg_hi:[0,0,1]
	v_pk_fma_f32 v[116:117], v[100:101], v[152:153], v[168:169]
	v_pk_fma_f32 v[100:101], v[100:101], v[234:235], v[132:133] neg_lo:[0,0,1] neg_hi:[0,0,1]
	v_pk_fma_f32 v[118:119], v[102:103], v[154:155], v[170:171]
	v_pk_fma_f32 v[102:103], v[102:103], v[236:237], v[134:135] neg_lo:[0,0,1] neg_hi:[0,0,1]
	v_pk_fma_f32 v[120:121], v[104:105], v[156:157], v[246:247]
	v_pk_fma_f32 v[104:105], v[104:105], v[238:239], v[136:137] neg_lo:[0,0,1] neg_hi:[0,0,1]
	v_pk_fma_f32 v[122:123], v[106:107], v[158:159], v[248:249]
	v_pk_fma_f32 v[106:107], v[106:107], v[240:241], v[138:139] neg_lo:[0,0,1] neg_hi:[0,0,1]
	v_pk_fma_f32 v[124:125], v[108:109], v[160:161], v[250:251]
	v_pk_fma_f32 v[108:109], v[108:109], v[242:243], v[140:141] neg_lo:[0,0,1] neg_hi:[0,0,1]
	v_pk_fma_f32 v[126:127], v[110:111], v[162:163], v[252:253]
	v_pk_fma_f32 v[110:111], v[110:111], v[244:245], v[142:143] neg_lo:[0,0,1] neg_hi:[0,0,1]
.Lpe_norope_3_L0:
	v_cvt_pk_bf16_f32 v96, v96, v97
	v_cvt_pk_bf16_f32 v97, v98, v99
	v_cvt_pk_bf16_f32 v98, v100, v101
	v_cvt_pk_bf16_f32 v99, v102, v103
	v_cvt_pk_bf16_f32 v100, v104, v105
	v_cvt_pk_bf16_f32 v101, v106, v107
	v_cvt_pk_bf16_f32 v102, v108, v109
	v_cvt_pk_bf16_f32 v103, v110, v111
	v_cvt_pk_bf16_f32 v112, v112, v113
	v_cvt_pk_bf16_f32 v113, v114, v115
	v_cvt_pk_bf16_f32 v114, v116, v117
	v_cvt_pk_bf16_f32 v115, v118, v119
	v_cvt_pk_bf16_f32 v116, v120, v121
	v_cvt_pk_bf16_f32 v117, v122, v123
	v_cvt_pk_bf16_f32 v118, v124, v125
	v_cvt_pk_bf16_f32 v119, v126, v127
	v_permlane32_swap_b32_e32 v96, v98
	v_permlane32_swap_b32_e32 v97, v99
	v_permlane32_swap_b32_e32 v100, v102
	v_permlane32_swap_b32_e32 v101, v103
	v_permlane32_swap_b32_e32 v112, v114
	v_permlane32_swap_b32_e32 v113, v115
	v_permlane32_swap_b32_e32 v116, v118
	v_permlane32_swap_b32_e32 v117, v119
	global_store_dwordx4 v181, v[96:99], s[74:75] offset:0
	global_store_dwordx4 v181, v[100:103], s[74:75] offset:32
	global_store_dwordx4 v181, v[112:115], s[74:75] offset:64
	global_store_dwordx4 v181, v[116:119], s[74:75] offset:96
	s_branch .Lpe_ret_L0
.Lpe_gates_L0:
	s_lshl_b32 s35, s98, 11
	s_add_u32 s35, s35, s30
	s_sub_u32 s35, s35, 0x900
	s_lshl_b32 s35, s35, 2
	v_readlane_b32 s82, v254, 12
	v_readlane_b32 s83, v254, 13
	s_add_u32 s82, s82, s35
	s_addc_u32 s83, s83, 0
	global_load_dwordx4 v[198:201], v146, s[82:83] offset:0
	global_load_dwordx4 v[202:205], v146, s[82:83] offset:32
	global_load_dwordx4 v[206:209], v146, s[82:83] offset:64
	global_load_dwordx4 v[210:213], v146, s[82:83] offset:96
	global_load_dwordx4 v[214:217], v146, s[82:83] offset:128
	global_load_dwordx4 v[218:221], v146, s[82:83] offset:160
	global_load_dwordx4 v[222:225], v146, s[82:83] offset:192
	global_load_dwordx4 v[226:229], v146, s[82:83] offset:224
	s_waitcnt vmcnt(8)
	v_mov_b32_e32 v197, 0x358637bd
	v_pk_add_f32 v[128:129], v[128:129], v[130:131]
	v_pk_add_f32 v[132:133], v[132:133], v[134:135]
	v_pk_add_f32 v[136:137], v[136:137], v[138:139]
	v_pk_add_f32 v[140:141], v[140:141], v[142:143]
	v_pk_add_f32 v[164:165], v[164:165], v[166:167]
	v_pk_add_f32 v[168:169], v[168:169], v[170:171]
	v_pk_add_f32 v[246:247], v[246:247], v[248:249]
	v_pk_add_f32 v[250:251], v[250:251], v[252:253]
	v_pk_add_f32 v[128:129], v[128:129], v[132:133]
	v_pk_add_f32 v[136:137], v[136:137], v[140:141]
	v_pk_add_f32 v[164:165], v[164:165], v[168:169]
	v_pk_add_f32 v[246:247], v[246:247], v[250:251]
	v_add_f32_e32 v128, v128, v129
	v_add_f32_e32 v136, v136, v137
	v_add_f32_e32 v164, v164, v165
	v_add_f32_e32 v246, v246, v247
	v_fmamk_f32 v128, v128, 0x3a800000, v197
	v_fmamk_f32 v136, v136, 0x3a800000, v197
	v_fmamk_f32 v164, v164, 0x3a800000, v197
	v_fmamk_f32 v246, v246, 0x3a800000, v197
	v_rsq_f32_e32 v172, v128
	v_rsq_f32_e32 v173, v136
	v_rsq_f32_e32 v174, v164
	v_rsq_f32_e32 v175, v246
	s_nop 0
	v_mul_f32_e32 v172, 0xbfb8aa3b, v172
	v_mul_f32_e32 v173, 0xbfb8aa3b, v173
	v_mul_f32_e32 v174, 0xbfb8aa3b, v174
	v_mul_f32_e32 v175, 0xbfb8aa3b, v175
	s_waitcnt vmcnt(0)
	v_mul_f32_e32 v198, 0xbfb8aa3b, v198
	v_mul_f32_e32 v199, 0xbfb8aa3b, v199
	v_mul_f32_e32 v200, 0xbfb8aa3b, v200
	v_mul_f32_e32 v201, 0xbfb8aa3b, v201
	v_mul_f32_e32 v202, 0xbfb8aa3b, v202
	v_mul_f32_e32 v203, 0xbfb8aa3b, v203
	v_mul_f32_e32 v204, 0xbfb8aa3b, v204
	v_mul_f32_e32 v205, 0xbfb8aa3b, v205
	v_mul_f32_e32 v206, 0xbfb8aa3b, v206
	v_mul_f32_e32 v207, 0xbfb8aa3b, v207
	v_mul_f32_e32 v208, 0xbfb8aa3b, v208
	v_mul_f32_e32 v209, 0xbfb8aa3b, v209
	v_mul_f32_e32 v210, 0xbfb8aa3b, v210
	v_mul_f32_e32 v211, 0xbfb8aa3b, v211
	v_mul_f32_e32 v212, 0xbfb8aa3b, v212
	v_mul_f32_e32 v213, 0xbfb8aa3b, v213
	v_mul_f32_e32 v214, 0xbfb8aa3b, v214
	v_mul_f32_e32 v215, 0xbfb8aa3b, v215
	v_mul_f32_e32 v216, 0xbfb8aa3b, v216
	v_mul_f32_e32 v217, 0xbfb8aa3b, v217
	v_mul_f32_e32 v218, 0xbfb8aa3b, v218
	v_mul_f32_e32 v219, 0xbfb8aa3b, v219
	v_mul_f32_e32 v220, 0xbfb8aa3b, v220
	v_mul_f32_e32 v221, 0xbfb8aa3b, v221
	v_mul_f32_e32 v222, 0xbfb8aa3b, v222
	v_mul_f32_e32 v223, 0xbfb8aa3b, v223
	v_mul_f32_e32 v224, 0xbfb8aa3b, v224
	v_mul_f32_e32 v225, 0xbfb8aa3b, v225
	v_mul_f32_e32 v226, 0xbfb8aa3b, v226
	v_mul_f32_e32 v227, 0xbfb8aa3b, v227
	v_mul_f32_e32 v228, 0xbfb8aa3b, v228
	v_mul_f32_e32 v229, 0xbfb8aa3b, v229
	v_pk_fma_f32 v[0:1], v[0:1], v[172:173], v[198:199] op_sel_hi:[1,0,1]
	v_pk_fma_f32 v[2:3], v[2:3], v[172:173], v[200:201] op_sel_hi:[1,0,1]
	v_pk_fma_f32 v[4:5], v[4:5], v[172:173], v[202:203] op_sel_hi:[1,0,1]
	v_pk_fma_f32 v[6:7], v[6:7], v[172:173], v[204:205] op_sel_hi:[1,0,1]
	v_pk_fma_f32 v[8:9], v[8:9], v[172:173], v[206:207] op_sel_hi:[1,0,1]
	v_pk_fma_f32 v[10:11], v[10:11], v[172:173], v[208:209] op_sel_hi:[1,0,1]
	v_pk_fma_f32 v[12:13], v[12:13], v[172:173], v[210:211] op_sel_hi:[1,0,1]
	v_pk_fma_f32 v[14:15], v[14:15], v[172:173], v[212:213] op_sel_hi:[1,0,1]
	v_pk_fma_f32 v[16:17], v[16:17], v[172:173], v[214:215] op_sel_hi:[1,0,1]
	v_pk_fma_f32 v[18:19], v[18:19], v[172:173], v[216:217] op_sel_hi:[1,0,1]
	v_pk_fma_f32 v[20:21], v[20:21], v[172:173], v[218:219] op_sel_hi:[1,0,1]
	v_pk_fma_f32 v[22:23], v[22:23], v[172:173], v[220:221] op_sel_hi:[1,0,1]
	v_pk_fma_f32 v[24:25], v[24:25], v[172:173], v[222:223] op_sel_hi:[1,0,1]
	v_pk_fma_f32 v[26:27], v[26:27], v[172:173], v[224:225] op_sel_hi:[1,0,1]
	v_pk_fma_f32 v[28:29], v[28:29], v[172:173], v[226:227] op_sel_hi:[1,0,1]
	v_pk_fma_f32 v[30:31], v[30:31], v[172:173], v[228:229] op_sel_hi:[1,0,1]
	v_exp_f32_e32 v0, v0
	v_exp_f32_e32 v1, v1
	v_exp_f32_e32 v2, v2
	v_exp_f32_e32 v3, v3
	v_exp_f32_e32 v4, v4
	v_exp_f32_e32 v5, v5
	v_exp_f32_e32 v6, v6
	v_exp_f32_e32 v7, v7
	v_exp_f32_e32 v8, v8
	v_exp_f32_e32 v9, v9
	v_exp_f32_e32 v10, v10
	v_exp_f32_e32 v11, v11
	v_exp_f32_e32 v12, v12
	v_exp_f32_e32 v13, v13
	v_exp_f32_e32 v14, v14
	v_exp_f32_e32 v15, v15
	v_exp_f32_e32 v16, v16
	v_exp_f32_e32 v17, v17
	v_exp_f32_e32 v18, v18
	v_exp_f32_e32 v19, v19
	v_exp_f32_e32 v20, v20
	v_exp_f32_e32 v21, v21
	v_exp_f32_e32 v22, v22
	v_exp_f32_e32 v23, v23
	v_exp_f32_e32 v24, v24
	v_exp_f32_e32 v25, v25
	v_exp_f32_e32 v26, v26
	v_exp_f32_e32 v27, v27
	v_exp_f32_e32 v28, v28
	v_exp_f32_e32 v29, v29
	v_exp_f32_e32 v30, v30
	v_exp_f32_e32 v31, v31
	v_pk_add_f32 v[0:1], v[0:1], 1.0 op_sel_hi:[1,0]
	v_pk_add_f32 v[2:3], v[2:3], 1.0 op_sel_hi:[1,0]
	v_pk_add_f32 v[4:5], v[4:5], 1.0 op_sel_hi:[1,0]
	v_pk_add_f32 v[6:7], v[6:7], 1.0 op_sel_hi:[1,0]
	v_pk_add_f32 v[8:9], v[8:9], 1.0 op_sel_hi:[1,0]
	v_pk_add_f32 v[10:11], v[10:11], 1.0 op_sel_hi:[1,0]
	v_pk_add_f32 v[12:13], v[12:13], 1.0 op_sel_hi:[1,0]
	v_pk_add_f32 v[14:15], v[14:15], 1.0 op_sel_hi:[1,0]
	v_pk_add_f32 v[16:17], v[16:17], 1.0 op_sel_hi:[1,0]
	v_pk_add_f32 v[18:19], v[18:19], 1.0 op_sel_hi:[1,0]
	v_pk_add_f32 v[20:21], v[20:21], 1.0 op_sel_hi:[1,0]
	v_pk_add_f32 v[22:23], v[22:23], 1.0 op_sel_hi:[1,0]
	v_pk_add_f32 v[24:25], v[24:25], 1.0 op_sel_hi:[1,0]
	v_pk_add_f32 v[26:27], v[26:27], 1.0 op_sel_hi:[1,0]
	v_pk_add_f32 v[28:29], v[28:29], 1.0 op_sel_hi:[1,0]
	v_pk_add_f32 v[30:31], v[30:31], 1.0 op_sel_hi:[1,0]
	v_rcp_f32_e32 v0, v0
	v_rcp_f32_e32 v1, v1
	v_rcp_f32_e32 v2, v2
	v_rcp_f32_e32 v3, v3
	v_rcp_f32_e32 v4, v4
	v_rcp_f32_e32 v5, v5
	v_rcp_f32_e32 v6, v6
	v_rcp_f32_e32 v7, v7
	v_rcp_f32_e32 v8, v8
	v_rcp_f32_e32 v9, v9
	v_rcp_f32_e32 v10, v10
	v_rcp_f32_e32 v11, v11
	v_rcp_f32_e32 v12, v12
	v_rcp_f32_e32 v13, v13
	v_rcp_f32_e32 v14, v14
	v_rcp_f32_e32 v15, v15
	v_rcp_f32_e32 v16, v16
	v_rcp_f32_e32 v17, v17
	v_rcp_f32_e32 v18, v18
	v_rcp_f32_e32 v19, v19
	v_rcp_f32_e32 v20, v20
	v_rcp_f32_e32 v21, v21
	v_rcp_f32_e32 v22, v22
	v_rcp_f32_e32 v23, v23
	v_rcp_f32_e32 v24, v24
	v_rcp_f32_e32 v25, v25
	v_rcp_f32_e32 v26, v26
	v_rcp_f32_e32 v27, v27
	v_rcp_f32_e32 v28, v28
	v_rcp_f32_e32 v29, v29
	v_rcp_f32_e32 v30, v30
	v_rcp_f32_e32 v31, v31
	s_nop 0
	v_cvt_pk_bf16_f32 v0, v0, v1
	v_cvt_pk_bf16_f32 v1, v2, v3
	v_cvt_pk_bf16_f32 v2, v4, v5
	v_cvt_pk_bf16_f32 v3, v6, v7
	v_cvt_pk_bf16_f32 v4, v8, v9
	v_cvt_pk_bf16_f32 v5, v10, v11
	v_cvt_pk_bf16_f32 v6, v12, v13
	v_cvt_pk_bf16_f32 v7, v14, v15
	v_cvt_pk_bf16_f32 v16, v16, v17
	v_cvt_pk_bf16_f32 v17, v18, v19
	v_cvt_pk_bf16_f32 v18, v20, v21
	v_cvt_pk_bf16_f32 v19, v22, v23
	v_cvt_pk_bf16_f32 v20, v24, v25
	v_cvt_pk_bf16_f32 v21, v26, v27
	v_cvt_pk_bf16_f32 v22, v28, v29
	v_cvt_pk_bf16_f32 v23, v30, v31
	v_permlane32_swap_b32_e32 v0, v2
	v_permlane32_swap_b32_e32 v1, v3
	v_permlane32_swap_b32_e32 v4, v6
	v_permlane32_swap_b32_e32 v5, v7
	v_permlane32_swap_b32_e32 v16, v18
	v_permlane32_swap_b32_e32 v17, v19
	v_permlane32_swap_b32_e32 v20, v22
	v_permlane32_swap_b32_e32 v21, v23
	global_store_dwordx4 v181, v[0:3], s[74:75] offset:0
	global_store_dwordx4 v181, v[4:7], s[74:75] offset:32
	global_store_dwordx4 v181, v[16:19], s[74:75] offset:64
	global_store_dwordx4 v181, v[20:23], s[74:75] offset:96
	s_add_u32 s74, s74, 0x44000
	s_addc_u32 s75, s75, 0
	v_pk_fma_f32 v[32:33], v[32:33], v[172:173], v[198:199] op_sel:[0,1,0] op_sel_hi:[1,1,1]
	v_pk_fma_f32 v[34:35], v[34:35], v[172:173], v[200:201] op_sel:[0,1,0] op_sel_hi:[1,1,1]
	v_pk_fma_f32 v[36:37], v[36:37], v[172:173], v[202:203] op_sel:[0,1,0] op_sel_hi:[1,1,1]
	v_pk_fma_f32 v[38:39], v[38:39], v[172:173], v[204:205] op_sel:[0,1,0] op_sel_hi:[1,1,1]
	v_pk_fma_f32 v[40:41], v[40:41], v[172:173], v[206:207] op_sel:[0,1,0] op_sel_hi:[1,1,1]
	v_pk_fma_f32 v[42:43], v[42:43], v[172:173], v[208:209] op_sel:[0,1,0] op_sel_hi:[1,1,1]
	v_pk_fma_f32 v[44:45], v[44:45], v[172:173], v[210:211] op_sel:[0,1,0] op_sel_hi:[1,1,1]
	v_pk_fma_f32 v[46:47], v[46:47], v[172:173], v[212:213] op_sel:[0,1,0] op_sel_hi:[1,1,1]
	v_pk_fma_f32 v[48:49], v[48:49], v[172:173], v[214:215] op_sel:[0,1,0] op_sel_hi:[1,1,1]
	v_pk_fma_f32 v[50:51], v[50:51], v[172:173], v[216:217] op_sel:[0,1,0] op_sel_hi:[1,1,1]
	v_pk_fma_f32 v[52:53], v[52:53], v[172:173], v[218:219] op_sel:[0,1,0] op_sel_hi:[1,1,1]
	v_pk_fma_f32 v[54:55], v[54:55], v[172:173], v[220:221] op_sel:[0,1,0] op_sel_hi:[1,1,1]
	v_pk_fma_f32 v[56:57], v[56:57], v[172:173], v[222:223] op_sel:[0,1,0] op_sel_hi:[1,1,1]
	v_pk_fma_f32 v[58:59], v[58:59], v[172:173], v[224:225] op_sel:[0,1,0] op_sel_hi:[1,1,1]
	v_pk_fma_f32 v[60:61], v[60:61], v[172:173], v[226:227] op_sel:[0,1,0] op_sel_hi:[1,1,1]
	v_pk_fma_f32 v[62:63], v[62:63], v[172:173], v[228:229] op_sel:[0,1,0] op_sel_hi:[1,1,1]
	v_exp_f32_e32 v32, v32
	v_exp_f32_e32 v33, v33
	v_exp_f32_e32 v34, v34
	v_exp_f32_e32 v35, v35
	v_exp_f32_e32 v36, v36
	v_exp_f32_e32 v37, v37
	v_exp_f32_e32 v38, v38
	v_exp_f32_e32 v39, v39
	v_exp_f32_e32 v40, v40
	v_exp_f32_e32 v41, v41
	v_exp_f32_e32 v42, v42
	v_exp_f32_e32 v43, v43
	v_exp_f32_e32 v44, v44
	v_exp_f32_e32 v45, v45
	v_exp_f32_e32 v46, v46
	v_exp_f32_e32 v47, v47
	v_exp_f32_e32 v48, v48
	v_exp_f32_e32 v49, v49
	v_exp_f32_e32 v50, v50
	v_exp_f32_e32 v51, v51
	v_exp_f32_e32 v52, v52
	v_exp_f32_e32 v53, v53
	v_exp_f32_e32 v54, v54
	v_exp_f32_e32 v55, v55
	v_exp_f32_e32 v56, v56
	v_exp_f32_e32 v57, v57
	v_exp_f32_e32 v58, v58
	v_exp_f32_e32 v59, v59
	v_exp_f32_e32 v60, v60
	v_exp_f32_e32 v61, v61
	v_exp_f32_e32 v62, v62
	v_exp_f32_e32 v63, v63
	v_pk_add_f32 v[32:33], v[32:33], 1.0 op_sel_hi:[1,0]
	v_pk_add_f32 v[34:35], v[34:35], 1.0 op_sel_hi:[1,0]
	v_pk_add_f32 v[36:37], v[36:37], 1.0 op_sel_hi:[1,0]
	v_pk_add_f32 v[38:39], v[38:39], 1.0 op_sel_hi:[1,0]
	v_pk_add_f32 v[40:41], v[40:41], 1.0 op_sel_hi:[1,0]
	v_pk_add_f32 v[42:43], v[42:43], 1.0 op_sel_hi:[1,0]
	v_pk_add_f32 v[44:45], v[44:45], 1.0 op_sel_hi:[1,0]
	v_pk_add_f32 v[46:47], v[46:47], 1.0 op_sel_hi:[1,0]
	v_pk_add_f32 v[48:49], v[48:49], 1.0 op_sel_hi:[1,0]
	v_pk_add_f32 v[50:51], v[50:51], 1.0 op_sel_hi:[1,0]
	v_pk_add_f32 v[52:53], v[52:53], 1.0 op_sel_hi:[1,0]
	v_pk_add_f32 v[54:55], v[54:55], 1.0 op_sel_hi:[1,0]
	v_pk_add_f32 v[56:57], v[56:57], 1.0 op_sel_hi:[1,0]
	v_pk_add_f32 v[58:59], v[58:59], 1.0 op_sel_hi:[1,0]
	v_pk_add_f32 v[60:61], v[60:61], 1.0 op_sel_hi:[1,0]
	v_pk_add_f32 v[62:63], v[62:63], 1.0 op_sel_hi:[1,0]
	v_rcp_f32_e32 v32, v32
	v_rcp_f32_e32 v33, v33
	v_rcp_f32_e32 v34, v34
	v_rcp_f32_e32 v35, v35
	v_rcp_f32_e32 v36, v36
	v_rcp_f32_e32 v37, v37
	v_rcp_f32_e32 v38, v38
	v_rcp_f32_e32 v39, v39
	v_rcp_f32_e32 v40, v40
	v_rcp_f32_e32 v41, v41
	v_rcp_f32_e32 v42, v42
	v_rcp_f32_e32 v43, v43
	v_rcp_f32_e32 v44, v44
	v_rcp_f32_e32 v45, v45
	v_rcp_f32_e32 v46, v46
	v_rcp_f32_e32 v47, v47
	v_rcp_f32_e32 v48, v48
	v_rcp_f32_e32 v49, v49
	v_rcp_f32_e32 v50, v50
	v_rcp_f32_e32 v51, v51
	v_rcp_f32_e32 v52, v52
	v_rcp_f32_e32 v53, v53
	v_rcp_f32_e32 v54, v54
	v_rcp_f32_e32 v55, v55
	v_rcp_f32_e32 v56, v56
	v_rcp_f32_e32 v57, v57
	v_rcp_f32_e32 v58, v58
	v_rcp_f32_e32 v59, v59
	v_rcp_f32_e32 v60, v60
	v_rcp_f32_e32 v61, v61
	v_rcp_f32_e32 v62, v62
	v_rcp_f32_e32 v63, v63
	s_nop 0
	v_cvt_pk_bf16_f32 v32, v32, v33
	v_cvt_pk_bf16_f32 v33, v34, v35
	v_cvt_pk_bf16_f32 v34, v36, v37
	v_cvt_pk_bf16_f32 v35, v38, v39
	v_cvt_pk_bf16_f32 v36, v40, v41
	v_cvt_pk_bf16_f32 v37, v42, v43
	v_cvt_pk_bf16_f32 v38, v44, v45
	v_cvt_pk_bf16_f32 v39, v46, v47
	v_cvt_pk_bf16_f32 v48, v48, v49
	v_cvt_pk_bf16_f32 v49, v50, v51
	v_cvt_pk_bf16_f32 v50, v52, v53
	v_cvt_pk_bf16_f32 v51, v54, v55
	v_cvt_pk_bf16_f32 v52, v56, v57
	v_cvt_pk_bf16_f32 v53, v58, v59
	v_cvt_pk_bf16_f32 v54, v60, v61
	v_cvt_pk_bf16_f32 v55, v62, v63
	v_permlane32_swap_b32_e32 v32, v34
	v_permlane32_swap_b32_e32 v33, v35
	v_permlane32_swap_b32_e32 v36, v38
	v_permlane32_swap_b32_e32 v37, v39
	v_permlane32_swap_b32_e32 v48, v50
	v_permlane32_swap_b32_e32 v49, v51
	v_permlane32_swap_b32_e32 v52, v54
	v_permlane32_swap_b32_e32 v53, v55
	global_store_dwordx4 v181, v[32:35], s[74:75] offset:0
	global_store_dwordx4 v181, v[36:39], s[74:75] offset:32
	global_store_dwordx4 v181, v[48:51], s[74:75] offset:64
	global_store_dwordx4 v181, v[52:55], s[74:75] offset:96
	s_add_u32 s74, s74, 0x44000
	s_addc_u32 s75, s75, 0
	v_pk_fma_f32 v[64:65], v[64:65], v[174:175], v[198:199] op_sel_hi:[1,0,1]
	v_pk_fma_f32 v[66:67], v[66:67], v[174:175], v[200:201] op_sel_hi:[1,0,1]
	v_pk_fma_f32 v[68:69], v[68:69], v[174:175], v[202:203] op_sel_hi:[1,0,1]
	v_pk_fma_f32 v[70:71], v[70:71], v[174:175], v[204:205] op_sel_hi:[1,0,1]
	v_pk_fma_f32 v[72:73], v[72:73], v[174:175], v[206:207] op_sel_hi:[1,0,1]
	v_pk_fma_f32 v[74:75], v[74:75], v[174:175], v[208:209] op_sel_hi:[1,0,1]
	v_pk_fma_f32 v[76:77], v[76:77], v[174:175], v[210:211] op_sel_hi:[1,0,1]
	v_pk_fma_f32 v[78:79], v[78:79], v[174:175], v[212:213] op_sel_hi:[1,0,1]
	v_pk_fma_f32 v[80:81], v[80:81], v[174:175], v[214:215] op_sel_hi:[1,0,1]
	v_pk_fma_f32 v[82:83], v[82:83], v[174:175], v[216:217] op_sel_hi:[1,0,1]
	v_pk_fma_f32 v[84:85], v[84:85], v[174:175], v[218:219] op_sel_hi:[1,0,1]
	v_pk_fma_f32 v[86:87], v[86:87], v[174:175], v[220:221] op_sel_hi:[1,0,1]
	v_pk_fma_f32 v[88:89], v[88:89], v[174:175], v[222:223] op_sel_hi:[1,0,1]
	v_pk_fma_f32 v[90:91], v[90:91], v[174:175], v[224:225] op_sel_hi:[1,0,1]
	v_pk_fma_f32 v[92:93], v[92:93], v[174:175], v[226:227] op_sel_hi:[1,0,1]
	v_pk_fma_f32 v[94:95], v[94:95], v[174:175], v[228:229] op_sel_hi:[1,0,1]
	v_exp_f32_e32 v64, v64
	v_exp_f32_e32 v65, v65
	v_exp_f32_e32 v66, v66
	v_exp_f32_e32 v67, v67
	v_exp_f32_e32 v68, v68
	v_exp_f32_e32 v69, v69
	v_exp_f32_e32 v70, v70
	v_exp_f32_e32 v71, v71
	v_exp_f32_e32 v72, v72
	v_exp_f32_e32 v73, v73
	v_exp_f32_e32 v74, v74
	v_exp_f32_e32 v75, v75
	v_exp_f32_e32 v76, v76
	v_exp_f32_e32 v77, v77
	v_exp_f32_e32 v78, v78
	v_exp_f32_e32 v79, v79
	v_exp_f32_e32 v80, v80
	v_exp_f32_e32 v81, v81
	v_exp_f32_e32 v82, v82
	v_exp_f32_e32 v83, v83
	v_exp_f32_e32 v84, v84
	v_exp_f32_e32 v85, v85
	v_exp_f32_e32 v86, v86
	v_exp_f32_e32 v87, v87
	v_exp_f32_e32 v88, v88
	v_exp_f32_e32 v89, v89
	v_exp_f32_e32 v90, v90
	v_exp_f32_e32 v91, v91
	v_exp_f32_e32 v92, v92
	v_exp_f32_e32 v93, v93
	v_exp_f32_e32 v94, v94
	v_exp_f32_e32 v95, v95
	v_pk_add_f32 v[64:65], v[64:65], 1.0 op_sel_hi:[1,0]
	v_pk_add_f32 v[66:67], v[66:67], 1.0 op_sel_hi:[1,0]
	v_pk_add_f32 v[68:69], v[68:69], 1.0 op_sel_hi:[1,0]
	v_pk_add_f32 v[70:71], v[70:71], 1.0 op_sel_hi:[1,0]
	v_pk_add_f32 v[72:73], v[72:73], 1.0 op_sel_hi:[1,0]
	v_pk_add_f32 v[74:75], v[74:75], 1.0 op_sel_hi:[1,0]
	v_pk_add_f32 v[76:77], v[76:77], 1.0 op_sel_hi:[1,0]
	v_pk_add_f32 v[78:79], v[78:79], 1.0 op_sel_hi:[1,0]
	v_pk_add_f32 v[80:81], v[80:81], 1.0 op_sel_hi:[1,0]
	v_pk_add_f32 v[82:83], v[82:83], 1.0 op_sel_hi:[1,0]
	v_pk_add_f32 v[84:85], v[84:85], 1.0 op_sel_hi:[1,0]
	v_pk_add_f32 v[86:87], v[86:87], 1.0 op_sel_hi:[1,0]
	v_pk_add_f32 v[88:89], v[88:89], 1.0 op_sel_hi:[1,0]
	v_pk_add_f32 v[90:91], v[90:91], 1.0 op_sel_hi:[1,0]
	v_pk_add_f32 v[92:93], v[92:93], 1.0 op_sel_hi:[1,0]
	v_pk_add_f32 v[94:95], v[94:95], 1.0 op_sel_hi:[1,0]
	v_rcp_f32_e32 v64, v64
	v_rcp_f32_e32 v65, v65
	v_rcp_f32_e32 v66, v66
	v_rcp_f32_e32 v67, v67
	v_rcp_f32_e32 v68, v68
	v_rcp_f32_e32 v69, v69
	v_rcp_f32_e32 v70, v70
	v_rcp_f32_e32 v71, v71
	v_rcp_f32_e32 v72, v72
	v_rcp_f32_e32 v73, v73
	v_rcp_f32_e32 v74, v74
	v_rcp_f32_e32 v75, v75
	v_rcp_f32_e32 v76, v76
	v_rcp_f32_e32 v77, v77
	v_rcp_f32_e32 v78, v78
	v_rcp_f32_e32 v79, v79
	v_rcp_f32_e32 v80, v80
	v_rcp_f32_e32 v81, v81
	v_rcp_f32_e32 v82, v82
	v_rcp_f32_e32 v83, v83
	v_rcp_f32_e32 v84, v84
	v_rcp_f32_e32 v85, v85
	v_rcp_f32_e32 v86, v86
	v_rcp_f32_e32 v87, v87
	v_rcp_f32_e32 v88, v88
	v_rcp_f32_e32 v89, v89
	v_rcp_f32_e32 v90, v90
	v_rcp_f32_e32 v91, v91
	v_rcp_f32_e32 v92, v92
	v_rcp_f32_e32 v93, v93
	v_rcp_f32_e32 v94, v94
	v_rcp_f32_e32 v95, v95
	s_nop 0
	v_cvt_pk_bf16_f32 v64, v64, v65
	v_cvt_pk_bf16_f32 v65, v66, v67
	v_cvt_pk_bf16_f32 v66, v68, v69
	v_cvt_pk_bf16_f32 v67, v70, v71
	v_cvt_pk_bf16_f32 v68, v72, v73
	v_cvt_pk_bf16_f32 v69, v74, v75
	v_cvt_pk_bf16_f32 v70, v76, v77
	v_cvt_pk_bf16_f32 v71, v78, v79
	v_cvt_pk_bf16_f32 v80, v80, v81
	v_cvt_pk_bf16_f32 v81, v82, v83
	v_cvt_pk_bf16_f32 v82, v84, v85
	v_cvt_pk_bf16_f32 v83, v86, v87
	v_cvt_pk_bf16_f32 v84, v88, v89
	v_cvt_pk_bf16_f32 v85, v90, v91
	v_cvt_pk_bf16_f32 v86, v92, v93
	v_cvt_pk_bf16_f32 v87, v94, v95
	v_permlane32_swap_b32_e32 v64, v66
	v_permlane32_swap_b32_e32 v65, v67
	v_permlane32_swap_b32_e32 v68, v70
	v_permlane32_swap_b32_e32 v69, v71
	v_permlane32_swap_b32_e32 v80, v82
	v_permlane32_swap_b32_e32 v81, v83
	v_permlane32_swap_b32_e32 v84, v86
	v_permlane32_swap_b32_e32 v85, v87
	global_store_dwordx4 v181, v[64:67], s[74:75] offset:0
	global_store_dwordx4 v181, v[68:71], s[74:75] offset:32
	global_store_dwordx4 v181, v[80:83], s[74:75] offset:64
	global_store_dwordx4 v181, v[84:87], s[74:75] offset:96
	s_add_u32 s74, s74, 0x44000
	s_addc_u32 s75, s75, 0
	v_pk_fma_f32 v[96:97], v[96:97], v[174:175], v[198:199] op_sel:[0,1,0] op_sel_hi:[1,1,1]
	v_pk_fma_f32 v[98:99], v[98:99], v[174:175], v[200:201] op_sel:[0,1,0] op_sel_hi:[1,1,1]
	v_pk_fma_f32 v[100:101], v[100:101], v[174:175], v[202:203] op_sel:[0,1,0] op_sel_hi:[1,1,1]
	v_pk_fma_f32 v[102:103], v[102:103], v[174:175], v[204:205] op_sel:[0,1,0] op_sel_hi:[1,1,1]
	v_pk_fma_f32 v[104:105], v[104:105], v[174:175], v[206:207] op_sel:[0,1,0] op_sel_hi:[1,1,1]
	v_pk_fma_f32 v[106:107], v[106:107], v[174:175], v[208:209] op_sel:[0,1,0] op_sel_hi:[1,1,1]
	v_pk_fma_f32 v[108:109], v[108:109], v[174:175], v[210:211] op_sel:[0,1,0] op_sel_hi:[1,1,1]
	v_pk_fma_f32 v[110:111], v[110:111], v[174:175], v[212:213] op_sel:[0,1,0] op_sel_hi:[1,1,1]
	v_pk_fma_f32 v[112:113], v[112:113], v[174:175], v[214:215] op_sel:[0,1,0] op_sel_hi:[1,1,1]
	v_pk_fma_f32 v[114:115], v[114:115], v[174:175], v[216:217] op_sel:[0,1,0] op_sel_hi:[1,1,1]
	v_pk_fma_f32 v[116:117], v[116:117], v[174:175], v[218:219] op_sel:[0,1,0] op_sel_hi:[1,1,1]
	v_pk_fma_f32 v[118:119], v[118:119], v[174:175], v[220:221] op_sel:[0,1,0] op_sel_hi:[1,1,1]
	v_pk_fma_f32 v[120:121], v[120:121], v[174:175], v[222:223] op_sel:[0,1,0] op_sel_hi:[1,1,1]
	v_pk_fma_f32 v[122:123], v[122:123], v[174:175], v[224:225] op_sel:[0,1,0] op_sel_hi:[1,1,1]
	v_pk_fma_f32 v[124:125], v[124:125], v[174:175], v[226:227] op_sel:[0,1,0] op_sel_hi:[1,1,1]
	v_pk_fma_f32 v[126:127], v[126:127], v[174:175], v[228:229] op_sel:[0,1,0] op_sel_hi:[1,1,1]
	v_exp_f32_e32 v96, v96
	v_exp_f32_e32 v97, v97
	v_exp_f32_e32 v98, v98
	v_exp_f32_e32 v99, v99
	v_exp_f32_e32 v100, v100
	v_exp_f32_e32 v101, v101
	v_exp_f32_e32 v102, v102
	v_exp_f32_e32 v103, v103
	v_exp_f32_e32 v104, v104
	v_exp_f32_e32 v105, v105
	v_exp_f32_e32 v106, v106
	v_exp_f32_e32 v107, v107
	v_exp_f32_e32 v108, v108
	v_exp_f32_e32 v109, v109
	v_exp_f32_e32 v110, v110
	v_exp_f32_e32 v111, v111
	v_exp_f32_e32 v112, v112
	v_exp_f32_e32 v113, v113
	v_exp_f32_e32 v114, v114
	v_exp_f32_e32 v115, v115
	v_exp_f32_e32 v116, v116
	v_exp_f32_e32 v117, v117
	v_exp_f32_e32 v118, v118
	v_exp_f32_e32 v119, v119
	v_exp_f32_e32 v120, v120
	v_exp_f32_e32 v121, v121
	v_exp_f32_e32 v122, v122
	v_exp_f32_e32 v123, v123
	v_exp_f32_e32 v124, v124
	v_exp_f32_e32 v125, v125
	v_exp_f32_e32 v126, v126
	v_exp_f32_e32 v127, v127
	v_pk_add_f32 v[96:97], v[96:97], 1.0 op_sel_hi:[1,0]
	v_pk_add_f32 v[98:99], v[98:99], 1.0 op_sel_hi:[1,0]
	v_pk_add_f32 v[100:101], v[100:101], 1.0 op_sel_hi:[1,0]
	v_pk_add_f32 v[102:103], v[102:103], 1.0 op_sel_hi:[1,0]
	v_pk_add_f32 v[104:105], v[104:105], 1.0 op_sel_hi:[1,0]
	v_pk_add_f32 v[106:107], v[106:107], 1.0 op_sel_hi:[1,0]
	v_pk_add_f32 v[108:109], v[108:109], 1.0 op_sel_hi:[1,0]
	v_pk_add_f32 v[110:111], v[110:111], 1.0 op_sel_hi:[1,0]
	v_pk_add_f32 v[112:113], v[112:113], 1.0 op_sel_hi:[1,0]
	v_pk_add_f32 v[114:115], v[114:115], 1.0 op_sel_hi:[1,0]
	v_pk_add_f32 v[116:117], v[116:117], 1.0 op_sel_hi:[1,0]
	v_pk_add_f32 v[118:119], v[118:119], 1.0 op_sel_hi:[1,0]
	v_pk_add_f32 v[120:121], v[120:121], 1.0 op_sel_hi:[1,0]
	v_pk_add_f32 v[122:123], v[122:123], 1.0 op_sel_hi:[1,0]
	v_pk_add_f32 v[124:125], v[124:125], 1.0 op_sel_hi:[1,0]
	v_pk_add_f32 v[126:127], v[126:127], 1.0 op_sel_hi:[1,0]
	v_rcp_f32_e32 v96, v96
	v_rcp_f32_e32 v97, v97
	v_rcp_f32_e32 v98, v98
	v_rcp_f32_e32 v99, v99
	v_rcp_f32_e32 v100, v100
	v_rcp_f32_e32 v101, v101
	v_rcp_f32_e32 v102, v102
	v_rcp_f32_e32 v103, v103
	v_rcp_f32_e32 v104, v104
	v_rcp_f32_e32 v105, v105
	v_rcp_f32_e32 v106, v106
	v_rcp_f32_e32 v107, v107
	v_rcp_f32_e32 v108, v108
	v_rcp_f32_e32 v109, v109
	v_rcp_f32_e32 v110, v110
	v_rcp_f32_e32 v111, v111
	v_rcp_f32_e32 v112, v112
	v_rcp_f32_e32 v113, v113
	v_rcp_f32_e32 v114, v114
	v_rcp_f32_e32 v115, v115
	v_rcp_f32_e32 v116, v116
	v_rcp_f32_e32 v117, v117
	v_rcp_f32_e32 v118, v118
	v_rcp_f32_e32 v119, v119
	v_rcp_f32_e32 v120, v120
	v_rcp_f32_e32 v121, v121
	v_rcp_f32_e32 v122, v122
	v_rcp_f32_e32 v123, v123
	v_rcp_f32_e32 v124, v124
	v_rcp_f32_e32 v125, v125
	v_rcp_f32_e32 v126, v126
	v_rcp_f32_e32 v127, v127
	s_nop 0
	v_cvt_pk_bf16_f32 v96, v96, v97
	v_cvt_pk_bf16_f32 v97, v98, v99
	v_cvt_pk_bf16_f32 v98, v100, v101
	v_cvt_pk_bf16_f32 v99, v102, v103
	v_cvt_pk_bf16_f32 v100, v104, v105
	v_cvt_pk_bf16_f32 v101, v106, v107
	v_cvt_pk_bf16_f32 v102, v108, v109
	v_cvt_pk_bf16_f32 v103, v110, v111
	v_cvt_pk_bf16_f32 v112, v112, v113
	v_cvt_pk_bf16_f32 v113, v114, v115
	v_cvt_pk_bf16_f32 v114, v116, v117
	v_cvt_pk_bf16_f32 v115, v118, v119
	v_cvt_pk_bf16_f32 v116, v120, v121
	v_cvt_pk_bf16_f32 v117, v122, v123
	v_cvt_pk_bf16_f32 v118, v124, v125
	v_cvt_pk_bf16_f32 v119, v126, v127
	v_permlane32_swap_b32_e32 v96, v98
	v_permlane32_swap_b32_e32 v97, v99
	v_permlane32_swap_b32_e32 v100, v102
	v_permlane32_swap_b32_e32 v101, v103
	v_permlane32_swap_b32_e32 v112, v114
	v_permlane32_swap_b32_e32 v113, v115
	v_permlane32_swap_b32_e32 v116, v118
	v_permlane32_swap_b32_e32 v117, v119
	global_store_dwordx4 v181, v[96:99], s[74:75] offset:0
	global_store_dwordx4 v181, v[100:103], s[74:75] offset:32
	global_store_dwordx4 v181, v[112:115], s[74:75] offset:64
	global_store_dwordx4 v181, v[116:119], s[74:75] offset:96
.Lpe_ret_L0:
	s_branch .LBB0_128
.Lpe_old_L0:
	s_lshl_b32 s0, s67, 8
	s_and_b32 s55, s0, 0x3800
	s_and_b32 s0, s25, 7
	s_lshl_b32 s56, s0, 8
	s_and_b32 s0, s61, 0xffffff00
	s_ashr_i32 s1, s0, 31
	s_lshl_b64 s[52:53], s[0:1], 1
	s_lshl_b32 s69, s24, 8
	s_or_b32 s46, s50, 0x80
	s_and_b32 s4, s68, 0x3fffff80
	s_cmpk_lg_i32 s4, 0x100
	s_cselect_b64 s[24:25], -1, 0
	s_cmpk_lg_i32 s50, 0x800
	s_cselect_b64 s[4:5], -1, 0
	s_and_b64 s[26:27], s[24:25], s[4:5]
	s_cmpk_lt_i32 s50, 0x200
	s_cselect_b64 s[28:29], -1, 0
	s_cmpk_gt_i32 s50, 0x1ff
	s_cselect_b64 s[30:31], -1, 0
	s_cmpk_gt_u32 s38, 0x3ff
	s_cselect_b64 s[34:35], -1, 0
	s_cmpk_gt_u32 s38, 0x7ff
	v_mov_b32_e32 v134, v144
	s_cselect_b64 s[36:37], -1, 0
	s_cmpk_lt_u32 s38, 0x800
	s_barrier
	s_cselect_b64 vcc, -1, 0
	v_lshrrev_b32_e32 v130, 1, v134
	s_cmpk_lt_u32 s50, 0x880
	v_and_b32_e32 v128, 0xc0, v134
	v_and_b32_e32 v130, 16, v130
	s_cselect_b64 s[38:39], -1, 0
	v_and_b32_e32 v129, 31, v134
	v_lshl_or_b32 v128, v128, 2, v130
	s_and_b64 s[4:5], s[38:39], exec
	v_mad_u32_u24 v200, v129, s63, v128
	v_lshlrev_b32_e32 v128, 3, v134
	s_cselect_b32 s40, 0xc0, s64
	v_and_b32_e32 v139, 0x7f, v134
	s_add_i32 s42, s50, 0xfffffc00
	v_and_b32_e32 v136, 56, v128
	v_lshlrev_b32_e32 v138, 5, v134
	v_or_b32_e32 v128, s42, v139
	s_lshr_b32 s16, s16, 3
	v_and_b32_e32 v146, 0x60, v138
	v_lshrrev_b32_e32 v128, 6, v128
	s_mul_i32 s16, s16, 10
	v_bfe_u32 v129, v134, 6, 1
	v_lshl_add_u64 v[148:149], s[8:9], 0, v[146:147]
	v_lshl_add_u64 v[150:151], s[10:11], 0, v[146:147]
	v_add_u32_e32 v146, s16, v128
	v_lshlrev_b32_e32 v130, 12, v134
	v_ashrrev_i32_e32 v140, 2, v134
	v_or_b32_e32 v135, 8, v129
	v_lshlrev_b64 v[128:129], 18, v[146:147]
	v_and_b32_e32 v146, 0x3f000, v130
	v_and_b32_e32 v130, 0xffffffe0, v140
	v_lshl_add_u64 v[128:129], s[2:3], 0, v[128:129]
	v_ashrrev_i32_e32 v131, 31, v130
	v_lshl_add_u64 v[128:129], v[128:129], 0, v[146:147]
	v_lshlrev_b64 v[132:133], 1, v[130:131]
	v_lshl_add_u64 v[152:153], v[128:129], 0, v[132:133]
	v_mul_lo_u32 v129, v130, s63
	v_lshlrev_b32_e32 v128, 2, v139
	v_or_b32_e32 v209, v129, v128
	v_lshlrev_b32_e32 v129, 2, v130
	v_add_u32_e32 v210, 0x20800, v129
	v_add_u32_e32 v213, 0x20810, v129
	v_add_u32_e32 v216, 0x20820, v129
	v_add_u32_e32 v219, 0x20830, v129
	v_add_u32_e32 v222, 0x20840, v129
	v_add_u32_e32 v225, 0x20850, v129
	v_add_u32_e32 v228, 0x20860, v129
	v_add_u32_e32 v231, 0x20870, v129
	v_or_b32_e32 v129, 31, v140
	v_mad_u64_u32 v[154:155], s[42:43], v129, s63, v[128:129]
	s_cmpk_lt_i32 s46, 0x200
	s_cselect_b64 s[42:43], -1, 0
	s_cmpk_gt_i32 s46, 0x1ff
	s_cselect_b64 s[44:45], -1, 0
	s_cmpk_lt_u32 s46, 0x880
	s_cselect_b64 s[46:47], -1, 0
	s_and_b64 s[58:59], s[46:47], exec
	s_cselect_b32 s48, 0xc0, s64
	s_add_i32 s57, s50, 0xfffffc80
	v_or_b32_e32 v128, s57, v139
	v_lshrrev_b32_e32 v130, 6, v128
	v_cndmask_b32_e32 v130, v135, v130, vcc
	v_readlane_b32 s72, v254, 6
	v_lshl_add_u32 v155, v129, 2, v196
	v_lshl_add_u64 v[128:129], s[2:3], 0, v[146:147]
	v_add_u32_e32 v146, s16, v130
	v_readlane_b32 s78, v254, 12
	s_lshl_b64 s[50:51], s[50:51], 2
	v_lshlrev_b64 v[130:131], 18, v[146:147]
	v_lshlrev_b32_e32 v146, 2, v136
	v_readlane_b32 s79, v254, 13
	v_readlane_b32 s80, v254, 14
	v_readlane_b32 s81, v254, 15
	s_add_u32 s50, s78, s50
	v_lshl_add_u64 v[128:129], v[128:129], 0, v[130:131]
	v_lshl_add_u64 v[158:159], s[80:81], 0, v[146:147]
	s_addc_u32 s51, s79, s51
	v_and_b32_e32 v146, 0x1e0, v138
	v_lshl_add_u64 v[156:157], v[128:129], 0, v[132:133]
	v_lshl_add_u64 v[128:129], s[50:51], 0, v[146:147]
	s_movk_i32 s50, 0xdc00
	v_ashrrev_i32_e32 v137, 4, v134
	s_mov_b32 s51, -1
	v_lshl_add_u64 v[160:161], v[128:129], 0, s[50:51]
	v_lshl_add_u64 v[162:163], v[128:129], 0, s[18:19]
	v_mul_lo_u32 v128, v137, s63
	v_and_b32_e32 v129, 15, v134
	s_movk_i32 s0, 0x80
	s_or_b32 s16, s56, s55
	v_lshl_add_u32 v234, v129, 5, v128
	v_lshl_or_b32 v128, v129, 4, s52
	v_mov_b32_e32 v129, s53
	v_ashrrev_i32_e32 v197, 8, v134
	v_cmp_gt_i32_e64 s[0:1], s0, v134
	v_add_u32_e32 v198, s69, v134
	v_lshl_add_u32 v199, v134, 2, v196
	v_add_u32_e32 v201, 0x18600, v200
	v_add_u32_e32 v202, 0x18620, v200
	v_add_u32_e32 v203, 0x18640, v200
	v_add_u32_e32 v204, 0x18660, v200
	v_add_u32_e32 v205, 0x18680, v200
	v_add_u32_e32 v206, 0x186a0, v200
	v_add_u32_e32 v207, 0x186c0, v200
	v_add_u32_e32 v208, 0x186e0, v200
	s_mov_b32 s54, 0
	v_cmp_gt_u32_e64 s[4:5], 32, v136
	v_add_u32_e32 v211, 0x820, v209
	v_add_u32_e32 v212, 0x1040, v209
	v_add_u32_e32 v214, 0x1860, v209
	v_add_u32_e32 v215, 0x2080, v209
	v_add_u32_e32 v217, 0x28a0, v209
	v_add_u32_e32 v218, 0x30c0, v209
	v_add_u32_e32 v220, 0x38e0, v209
	v_add_u32_e32 v221, 0x4100, v209
	v_add_u32_e32 v223, 0x4920, v209
	v_add_u32_e32 v224, 0x5140, v209
	v_add_u32_e32 v226, 0x5960, v209
	v_add_u32_e32 v227, 0x6180, v209
	v_add_u32_e32 v229, 0x69a0, v209
	v_add_u32_e32 v230, 0x71c0, v209
	v_add_u32_e32 v232, 0x79e0, v209
	v_add_u32_e32 v233, s16, v137
	v_lshl_add_u32 v235, v137, 2, v196
	v_lshl_add_u64 v[164:165], s[12:13], 0, v[128:129]
	v_add_u32_e32 v236, 0x200, v234
	v_lshl_add_u64 v[166:167], s[14:15], 0, v[128:129]
	s_mov_b64 s[50:51], -1
	v_readlane_b32 s73, v254, 7
	v_readlane_b32 s74, v254, 8
	v_readlane_b32 s75, v254, 9
	v_readlane_b32 s76, v254, 10
	v_readlane_b32 s77, v254, 11
	v_readlane_b32 s82, v254, 16
	v_readlane_b32 s83, v254, 17
	v_readlane_b32 s84, v254, 18
	v_readlane_b32 s85, v254, 19
	v_readlane_b32 s86, v254, 20
	v_readlane_b32 s87, v254, 21
	s_branch .LBB0_137

.LBB0_724:
	s_lshl_b32 s4, s86, 3
	s_and_b32 s16, s4, 56
	s_bfe_u32 s4, s86, 0x30003
	s_or_b32 s24, s16, s4
	s_lshl_b32 s33, s86, 2
	s_lshr_b32 s25, s86, 3
	s_and_b32 s48, s33, 0xffffff00
	s_lshl_b32 s4, s24, 19
	s_add_u32 s6, s21, s4
	s_addc_u32 s7, s47, 0
	s_ashr_i32 s49, s48, 31
	s_lshl_b64 s[4:5], s[48:49], 11
	s_add_u32 s26, s60, s4
	v_readfirstlane_b32 s4, v176
	s_addc_u32 s27, s61, s5
	s_ashr_i32 s28, s4, 6
	s_lshl_b32 s4, s28, 5
	s_ashr_i32 s5, s4, 31
	s_lshl_b64 s[4:5], s[4:5], 11
	s_add_u32 s6, s6, s4
	s_addc_u32 s7, s7, s5
	s_add_u32 s4, s26, s4
	s_addc_u32 s5, s27, s5
	s_lshl_b32 s26, s28, 12
	s_add_i32 s27, s26, 0x8000
	s_and_b32 s81, s24, 7
	s_lshl_b32 s81, s81, 8
	s_add_u32 s6, s6, s81
	s_addc_u32 s7, s7, 0
	s_add_u32 s4, s4, s81
	s_addc_u32 s5, s5, 0
	s_add_u32 s28, s6, 0x4000
	s_barrier
	s_mov_b32 m0, s26
	global_load_lds_dwordx4 v177, s[6:7]
	s_addc_u32 s29, s7, 0
	s_or_b32 s30, s26, 0x400
	s_mov_b32 m0, s30
	global_load_lds_dwordx4 v185, s[28:29]
	s_add_u32 s28, s6, 0x8000
	s_addc_u32 s29, s7, 0
	s_or_b32 s30, s26, 0x800
	s_mov_b32 m0, s30
	global_load_lds_dwordx4 v177, s[28:29]
	s_add_u32 s28, s6, 0xc000
	s_addc_u32 s29, s7, 0
	s_or_b32 s30, s26, 0xc00
	s_mov_b32 m0, s30
	global_load_lds_dwordx4 v185, s[28:29]
	s_add_u32 s28, s4, 0x4000
	s_mov_b32 m0, s27
	global_load_lds_dwordx4 v177, s[4:5]
	s_addc_u32 s29, s5, 0
	s_add_i32 s27, s26, 0x8400
	s_mov_b32 m0, s27
	global_load_lds_dwordx4 v185, s[28:29]
	s_add_u32 s28, s4, 0x8000
	s_addc_u32 s29, s5, 0
	s_add_i32 s27, s26, 0x8800
	s_mov_b32 m0, s27
	global_load_lds_dwordx4 v177, s[28:29]
	s_add_u32 s28, s4, 0xc000
	s_addc_u32 s29, s5, 0
	s_add_i32 s27, s26, 0x8c00
	s_mov_b32 m0, s27
	global_load_lds_dwordx4 v185, s[28:29]
	s_sub_u32 s6, s6, s81
	s_subb_u32 s7, s7, 0
	s_sub_u32 s4, s4, s81
	s_subb_u32 s5, s5, 0
	s_add_u32 s27, s4, 0xc000
	s_addc_u32 s28, s5, 0
	s_add_u32 s29, s4, 0x8000
	s_addc_u32 s30, s5, 0
	s_add_u32 s31, s4, 0x4000
	s_addc_u32 s34, s5, 0
	s_add_u32 s35, s4, 0x0
	s_addc_u32 s36, s5, 0
	s_add_u32 s37, s6, 0xc000
	s_addc_u32 s38, s7, 0
	s_add_u32 s39, s6, 0x8000
	s_addc_u32 s40, s7, 0
	s_add_u32 s41, s6, 0x4000
	s_addc_u32 s42, s7, 0
	s_add_u32 s43, s6, 0x0
	s_addc_u32 s44, s7, 0
	s_mov_b64 s[4:5], 0
	s_mov_b32 s46, s17
	s_mov_b32 s45, s17
	v_mov_b32_e32 v0, v145
	v_mov_b32_e32 v1, v145
	v_mov_b32_e32 v2, v145
	v_mov_b32_e32 v3, v145
	v_mov_b32_e32 v4, v145
	v_mov_b32_e32 v5, v145
	v_mov_b32_e32 v6, v145
	v_mov_b32_e32 v7, v145
	v_mov_b32_e32 v8, v145
	v_mov_b32_e32 v9, v145
	v_mov_b32_e32 v10, v145
	v_mov_b32_e32 v11, v145
	v_mov_b32_e32 v12, v145
	v_mov_b32_e32 v13, v145
	v_mov_b32_e32 v14, v145
	v_mov_b32_e32 v15, v145
	v_mov_b32_e32 v16, v145
	v_mov_b32_e32 v17, v145
	v_mov_b32_e32 v18, v145
	v_mov_b32_e32 v19, v145
	v_mov_b32_e32 v20, v145
	v_mov_b32_e32 v21, v145
	v_mov_b32_e32 v22, v145
	v_mov_b32_e32 v23, v145
	v_mov_b32_e32 v24, v145
	v_mov_b32_e32 v25, v145
	v_mov_b32_e32 v26, v145
	v_mov_b32_e32 v27, v145
	v_mov_b32_e32 v28, v145
	v_mov_b32_e32 v29, v145
	v_mov_b32_e32 v30, v145
	v_mov_b32_e32 v31, v145
	v_mov_b32_e32 v32, v145
	v_mov_b32_e32 v33, v145
	v_mov_b32_e32 v34, v145
	v_mov_b32_e32 v35, v145
	v_mov_b32_e32 v36, v145
	v_mov_b32_e32 v37, v145
	v_mov_b32_e32 v38, v145
	v_mov_b32_e32 v39, v145
	v_mov_b32_e32 v40, v145
	v_mov_b32_e32 v41, v145
	v_mov_b32_e32 v42, v145
	v_mov_b32_e32 v43, v145
	v_mov_b32_e32 v44, v145
	v_mov_b32_e32 v45, v145
	v_mov_b32_e32 v46, v145
	v_mov_b32_e32 v47, v145
	v_mov_b32_e32 v48, v145
	v_mov_b32_e32 v49, v145
	v_mov_b32_e32 v50, v145
	v_mov_b32_e32 v51, v145
	v_mov_b32_e32 v52, v145
	v_mov_b32_e32 v53, v145
	v_mov_b32_e32 v54, v145
	v_mov_b32_e32 v55, v145
	v_mov_b32_e32 v56, v145
	v_mov_b32_e32 v57, v145
	v_mov_b32_e32 v58, v145
	v_mov_b32_e32 v59, v145
	v_mov_b32_e32 v60, v145
	v_mov_b32_e32 v61, v145
	v_mov_b32_e32 v62, v145
	v_mov_b32_e32 v63, v145
	v_mov_b32_e32 v64, v145
	v_mov_b32_e32 v65, v145
	v_mov_b32_e32 v66, v145
	v_mov_b32_e32 v67, v145
	v_mov_b32_e32 v68, v145
	v_mov_b32_e32 v69, v145
	v_mov_b32_e32 v70, v145
	v_mov_b32_e32 v71, v145
	v_mov_b32_e32 v72, v145
	v_mov_b32_e32 v73, v145
	v_mov_b32_e32 v74, v145
	v_mov_b32_e32 v75, v145
	v_mov_b32_e32 v76, v145
	v_mov_b32_e32 v77, v145
	v_mov_b32_e32 v78, v145
	v_mov_b32_e32 v79, v145
	v_mov_b32_e32 v80, v145
	v_mov_b32_e32 v81, v145
	v_mov_b32_e32 v82, v145
	v_mov_b32_e32 v83, v145
	v_mov_b32_e32 v84, v145
	v_mov_b32_e32 v85, v145
	v_mov_b32_e32 v86, v145
	v_mov_b32_e32 v87, v145
	v_mov_b32_e32 v88, v145
	v_mov_b32_e32 v89, v145
	v_mov_b32_e32 v90, v145
	v_mov_b32_e32 v91, v145
	v_mov_b32_e32 v92, v145
	v_mov_b32_e32 v93, v145
	v_mov_b32_e32 v94, v145
	v_mov_b32_e32 v95, v145
	v_mov_b32_e32 v96, v145
	v_mov_b32_e32 v97, v145
	v_mov_b32_e32 v98, v145
	v_mov_b32_e32 v99, v145
	v_mov_b32_e32 v100, v145
	v_mov_b32_e32 v101, v145
	v_mov_b32_e32 v102, v145
	v_mov_b32_e32 v103, v145
	v_mov_b32_e32 v104, v145
	v_mov_b32_e32 v105, v145
	v_mov_b32_e32 v106, v145
	v_mov_b32_e32 v107, v145
	v_mov_b32_e32 v108, v145
	v_mov_b32_e32 v109, v145
	v_mov_b32_e32 v110, v145
	v_mov_b32_e32 v111, v145
	v_mov_b32_e32 v112, v145
	v_mov_b32_e32 v113, v145
	v_mov_b32_e32 v114, v145
	v_mov_b32_e32 v115, v145
	v_mov_b32_e32 v116, v145
	v_mov_b32_e32 v117, v145
	v_mov_b32_e32 v118, v145
	v_mov_b32_e32 v119, v145
	v_mov_b32_e32 v120, v145
	v_mov_b32_e32 v121, v145
	v_mov_b32_e32 v122, v145
	v_mov_b32_e32 v123, v145
	v_mov_b32_e32 v124, v145
	v_mov_b32_e32 v125, v145
	v_mov_b32_e32 v126, v145
	v_mov_b32_e32 v127, v145
	s_branch .LBB0_726

.LBB0_728:
	s_andn2_b64 vcc, exec, s[6:7]
	s_cbranch_vccnz .LBB0_725
	s_add_i32 s50, s46, 0x10000
	s_and_b32 s6, s50, 0x10000
	s_add_i32 s51, s6, s26
	s_add_i32 s52, s51, 0x8000
	s_add_u32 s82, s4, s81
	s_addk_i32 s82, 0x80
	s_and_b32 s82, s82, 0x7ff
	s_mov_b32 s83, 0
	s_add_u32 s6, s43, s82
	s_addc_u32 s7, s44, s83
	s_mov_b32 m0, s51
	global_load_lds_dwordx4 v177, s[6:7]
	s_add_u32 s6, s41, s82
	s_addc_u32 s7, s42, s83
	s_add_i32 s53, s51, 0x400
	s_mov_b32 m0, s53
	global_load_lds_dwordx4 v185, s[6:7]
	s_add_u32 s6, s39, s82
	s_addc_u32 s7, s40, s83
	s_add_i32 s53, s51, 0x800
	s_mov_b32 m0, s53
	global_load_lds_dwordx4 v177, s[6:7]
	s_add_u32 s6, s37, s82
	s_addc_u32 s7, s38, s83
	s_add_i32 s53, s51, 0xc00
	s_mov_b32 m0, s53
	global_load_lds_dwordx4 v185, s[6:7]
	s_add_u32 s6, s35, s82
	s_addc_u32 s7, s36, s83
	s_mov_b32 m0, s52
	global_load_lds_dwordx4 v177, s[6:7]
	s_add_u32 s6, s31, s82
	s_addc_u32 s7, s34, s83
	s_add_i32 s52, s51, 0x8400
	s_mov_b32 m0, s52
	global_load_lds_dwordx4 v185, s[6:7]
	s_add_u32 s6, s29, s82
	s_addc_u32 s7, s30, s83
	s_add_i32 s52, s51, 0x8800
	s_mov_b32 m0, s52
	global_load_lds_dwordx4 v177, s[6:7]
	s_add_u32 s6, s27, s82
	s_addc_u32 s7, s28, s83
	s_add_i32 s51, s51, 0x8c00
	s_mov_b32 m0, s51
	global_load_lds_dwordx4 v185, s[6:7]
	s_branch .LBB0_725
.LBB0_730:
	s_lshr_b32 s4, s86, 6
	s_sub_u32 s4, s4, 4
	s_cmp_lt_u32 s4, 2
	s_cbranch_scc1 .Lpe_old_L1
	s_cmp_eq_u32 s4, 4
	s_cbranch_scc1 .Lpe_old_L1
	s_mov_b32 s98, 1
	s_mov_b32 s99, s86

.Lpe_ret_L1:
	s_branch .LBB0_723
.Lpe_old_L1:
	s_lshl_b32 s4, s85, 8
	s_and_b32 s52, s4, 0x3800
	s_and_b32 s4, s25, 7
	s_lshl_b32 s53, s4, 8
	s_and_b32 s4, s62, 0xffffff00
	s_ashr_i32 s5, s4, 31
	s_lshl_b64 s[50:51], s[4:5], 1
	s_lshl_b32 s87, s24, 8
	s_or_b32 s42, s48, 0x80
	s_and_b32 s6, s86, 0x3fffff80
	s_cmpk_lg_i32 s6, 0x100
	s_cselect_b64 s[24:25], -1, 0
	s_cmpk_lg_i32 s48, 0x800
	s_cselect_b64 s[6:7], -1, 0
	s_and_b64 s[26:27], s[24:25], s[6:7]
	s_cmpk_lt_i32 s48, 0x200
	v_mov_b32_e32 v134, v176
	s_cselect_b64 s[28:29], -1, 0
	s_cmpk_gt_i32 s48, 0x1ff
	s_barrier
	s_cselect_b64 s[30:31], -1, 0
	v_lshrrev_b32_e32 v130, 1, v134
	s_cmpk_gt_u32 s33, 0x3ff
	v_and_b32_e32 v128, 0xc0, v134
	v_and_b32_e32 v130, 16, v130
	s_cselect_b64 s[34:35], -1, 0
	s_cmpk_gt_u32 s33, 0x7ff
	v_and_b32_e32 v129, 31, v134
	v_lshl_or_b32 v128, v128, 2, v130
	s_cselect_b64 s[36:37], -1, 0
	s_cmpk_lt_u32 s33, 0x800
	v_mad_u32_u24 v197, v129, s64, v128
	v_lshlrev_b32_e32 v128, 3, v134
	s_cselect_b64 vcc, -1, 0
	s_add_i32 s33, s48, 0xfffffc00
	v_and_b32_e32 v139, 0x7f, v134
	s_lshr_b32 s16, s16, 3
	v_and_b32_e32 v136, 56, v128
	v_lshlrev_b32_e32 v138, 5, v134
	v_or_b32_e32 v128, s33, v139
	v_and_b32_e32 v144, 0x60, v138
	v_lshrrev_b32_e32 v128, 6, v128
	s_mul_i32 s16, s16, 10
	v_bfe_u32 v129, v134, 6, 1
	v_lshl_add_u64 v[146:147], s[8:9], 0, v[144:145]
	v_lshl_add_u64 v[148:149], s[10:11], 0, v[144:145]
	v_add_u32_e32 v144, s16, v128
	v_lshlrev_b32_e32 v130, 12, v134
	v_ashrrev_i32_e32 v140, 2, v134
	v_or_b32_e32 v135, 8, v129
	v_lshlrev_b64 v[128:129], 18, v[144:145]
	v_and_b32_e32 v144, 0x3f000, v130
	v_and_b32_e32 v130, 0xffffffe0, v140
	v_lshl_add_u64 v[128:129], s[0:1], 0, v[128:129]
	v_ashrrev_i32_e32 v131, 31, v130
	s_cmpk_lt_i32 s42, 0x200
	v_lshl_add_u64 v[128:129], v[128:129], 0, v[144:145]
	v_lshlrev_b64 v[132:133], 1, v[130:131]
	s_cselect_b64 s[38:39], -1, 0
	s_cmpk_gt_i32 s42, 0x1ff
	v_lshl_add_u64 v[150:151], v[128:129], 0, v[132:133]
	v_mul_lo_u32 v129, v130, s64
	v_lshlrev_b32_e32 v128, 2, v139
	s_cselect_b64 s[40:41], -1, 0
	s_cmpk_lt_u32 s42, 0x880
	v_or_b32_e32 v209, v129, v128
	v_lshlrev_b32_e32 v129, 2, v130
	s_cselect_b64 s[42:43], -1, 0
	s_add_i32 s46, s48, 0xfffffc80
	v_add_u32_e32 v210, 0x20800, v129
	v_add_u32_e32 v213, 0x20810, v129
	v_add_u32_e32 v216, 0x20820, v129
	v_add_u32_e32 v219, 0x20830, v129
	v_add_u32_e32 v222, 0x20840, v129
	v_add_u32_e32 v225, 0x20850, v129
	v_add_u32_e32 v228, 0x20860, v129
	v_add_u32_e32 v231, 0x20870, v129
	v_or_b32_e32 v129, 31, v140
	s_cmpk_lt_u32 s48, 0x880
	v_mad_u64_u32 v[152:153], s[54:55], v129, s64, v[128:129]
	v_or_b32_e32 v128, s46, v139
	s_cselect_b64 s[44:45], -1, 0
	v_lshrrev_b32_e32 v130, 6, v128
	v_cndmask_b32_e32 v130, v135, v130, vcc
	s_mov_b64 s[58:59], s[70:71]
	v_readlane_b32 s68, v254, 6
	s_and_b64 s[54:55], s[44:45], exec
	v_lshl_add_u32 v153, v129, 2, v193
	v_lshl_add_u64 v[128:129], s[0:1], 0, v[144:145]
	v_add_u32_e32 v144, s16, v130
	v_readlane_b32 s74, v254, 12
	s_cselect_b32 s46, s65, 0x200
	s_lshl_b64 s[48:49], s[48:49], 2
	v_lshlrev_b64 v[130:131], 18, v[144:145]
	v_lshlrev_b32_e32 v144, 2, v136
	v_readlane_b32 s75, v254, 13
	v_readlane_b32 s76, v254, 14
	v_readlane_b32 s77, v254, 15
	s_add_u32 s48, s74, s48
	v_lshl_add_u64 v[128:129], v[128:129], 0, v[130:131]
	v_lshl_add_u64 v[156:157], s[76:77], 0, v[144:145]
	s_addc_u32 s49, s75, s49
	v_and_b32_e32 v144, 0x1e0, v138
	v_lshl_add_u64 v[154:155], v[128:129], 0, v[132:133]
	v_lshl_add_u64 v[128:129], s[48:49], 0, v[144:145]
	s_movk_i32 s48, 0xfc00
	v_ashrrev_i32_e32 v137, 4, v134
	s_mov_b32 s49, -1
	v_lshl_add_u64 v[158:159], v[128:129], 0, s[48:49]
	s_and_b64 s[48:49], s[42:43], exec
	v_lshl_add_u64 v[160:161], v[128:129], 0, s[18:19]
	v_mul_lo_u32 v128, v137, s64
	v_and_b32_e32 v129, 15, v134
	s_movk_i32 s4, 0x80
	v_readlane_b32 s70, v254, 8
	v_readlane_b32 s71, v254, 9
	s_cselect_b32 s48, s65, 0x200
	s_or_b32 s33, s53, s52
	v_lshl_add_u32 v234, v129, 5, v128
	v_lshl_or_b32 v128, v129, 4, s50
	v_mov_b32_e32 v129, s51
	v_ashrrev_i32_e32 v194, 8, v134
	v_cmp_gt_i32_e64 s[4:5], s4, v134
	v_add_u32_e32 v195, s87, v134
	v_lshl_add_u32 v196, v134, 2, v193
	v_add_u32_e32 v198, 0x104a0, v197
	v_add_u32_e32 v199, 0x104c0, v197
	v_add_u32_e32 v200, 0x104e0, v197
	v_add_u32_e32 v201, 0x18600, v197
	v_add_u32_e32 v202, 0x18620, v197
	v_add_u32_e32 v203, 0x18640, v197
	v_add_u32_e32 v204, 0x18660, v197
	v_add_u32_e32 v205, 0x18680, v197
	v_add_u32_e32 v206, 0x186a0, v197
	v_add_u32_e32 v207, 0x186c0, v197
	v_add_u32_e32 v208, 0x186e0, v197
	v_cmp_gt_u32_e64 s[6:7], 32, v136
	v_add_u32_e32 v211, 0x820, v209
	v_add_u32_e32 v212, 0x1040, v209
	v_add_u32_e32 v214, 0x1860, v209
	v_add_u32_e32 v215, 0x2080, v209
	v_add_u32_e32 v217, 0x28a0, v209
	v_add_u32_e32 v218, 0x30c0, v209
	v_add_u32_e32 v220, 0x38e0, v209
	v_add_u32_e32 v221, 0x4100, v209
	v_add_u32_e32 v223, 0x4920, v209
	v_add_u32_e32 v224, 0x5140, v209
	v_add_u32_e32 v226, 0x5960, v209
	v_add_u32_e32 v227, 0x6180, v209
	v_add_u32_e32 v229, 0x69a0, v209
	v_add_u32_e32 v230, 0x71c0, v209
	v_add_u32_e32 v232, 0x79e0, v209
	s_mov_b32 s16, 0
	s_mov_b64 s[70:71], s[58:59]
	v_add_u32_e32 v233, s33, v137
	v_lshl_add_u32 v235, v137, 2, v193
	v_lshl_add_u64 v[162:163], s[12:13], 0, v[128:129]
	v_add_u32_e32 v236, 0x200, v234
	v_lshl_add_u64 v[164:165], s[14:15], 0, v[128:129]
	s_mov_b64 s[50:51], -1
	v_readlane_b32 s69, v254, 7
	v_readlane_b32 s72, v254, 10
	v_readlane_b32 s73, v254, 11
	v_readlane_b32 s78, v254, 16
	v_readlane_b32 s79, v254, 17
	v_readlane_b32 s80, v254, 18
	v_readlane_b32 s81, v254, 19
	v_readlane_b32 s82, v254, 20
	v_readlane_b32 s83, v254, 21
	s_branch .LBB0_732

	.amdhsa_kernel _Z11mega_kernel6Params
		.amdhsa_group_segment_fixed_size 147472
		.amdhsa_private_segment_fixed_size 0
		.amdhsa_kernarg_size 408
		.amdhsa_user_sgpr_count 2
		.amdhsa_user_sgpr_dispatch_ptr 0
		.amdhsa_user_sgpr_queue_ptr 0
		.amdhsa_user_sgpr_kernarg_segment_ptr 1
		.amdhsa_user_sgpr_dispatch_id 0
		.amdhsa_user_sgpr_kernarg_preload_length 0
		.amdhsa_user_sgpr_kernarg_preload_offset 0
		.amdhsa_user_sgpr_private_segment_size 0
		.amdhsa_uses_dynamic_stack 0
		.amdhsa_enable_private_segment 0
		.amdhsa_system_sgpr_workgroup_id_x 1
		.amdhsa_system_sgpr_workgroup_id_y 0
		.amdhsa_system_sgpr_workgroup_id_z 0
		.amdhsa_system_sgpr_workgroup_info 0
		.amdhsa_system_vgpr_workitem_id 2
		.amdhsa_next_free_vgpr 256
		.amdhsa_next_free_sgpr 102
		.amdhsa_accum_offset 256
		.amdhsa_reserve_vcc 1
		.amdhsa_float_round_mode_32 0
		.amdhsa_float_round_mode_16_64 0
		.amdhsa_float_denorm_mode_32 3
		.amdhsa_float_denorm_mode_16_64 3
		.amdhsa_dx10_clamp 1
		.amdhsa_ieee_mode 1
		.amdhsa_fp16_overflow 0
		.amdhsa_tg_split 0
		.amdhsa_exception_fp_ieee_invalid_op 0
		.amdhsa_exception_fp_denorm_src 0
		.amdhsa_exception_fp_ieee_div_zero 0
		.amdhsa_exception_fp_ieee_overflow 0
		.amdhsa_exception_fp_ieee_underflow 0
		.amdhsa_exception_fp_ieee_inexact 0
		.amdhsa_exception_int_div_zero 0
	.end_amdhsa_kernel

amdhsa.kernels:
  - .agpr_count:     0
    .args:
      - .offset:         0
        .size:           152
        .value_kind:     by_value
      - .offset:         152
        .size:           4
        .value_kind:     hidden_block_count_x
      - .offset:         156
        .size:           4
        .value_kind:     hidden_block_count_y
      - .offset:         160
        .size:           4
        .value_kind:     hidden_block_count_z
      - .offset:         164
        .size:           2
        .value_kind:     hidden_group_size_x
      - .offset:         166
        .size:           2
        .value_kind:     hidden_group_size_y
      - .offset:         168
        .size:           2
        .value_kind:     hidden_group_size_z
      - .offset:         170
        .size:           2
        .value_kind:     hidden_remainder_x
      - .offset:         172
        .size:           2
        .value_kind:     hidden_remainder_y
      - .offset:         174
        .size:           2
        .value_kind:     hidden_remainder_z
      - .offset:         192
        .size:           8
        .value_kind:     hidden_global_offset_x
      - .offset:         200
        .size:           8
        .value_kind:     hidden_global_offset_y
      - .offset:         208
        .size:           8
        .value_kind:     hidden_global_offset_z
      - .offset:         216
        .size:           2
        .value_kind:     hidden_grid_dims
      - .offset:         240
        .size:           8
        .value_kind:     hidden_multigrid_sync_arg
    .group_segment_fixed_size: 147472
    .kernarg_segment_align: 8
    .kernarg_segment_size: 408
    .language:       OpenCL C
    .language_version:
      - 2
      - 0
    .max_flat_workgroup_size: 512
    .name:           _Z11mega_kernel6Params
    .private_segment_fixed_size: 0
    .sgpr_count:     108
    .sgpr_spill_count: 89
    .symbol:         _Z11mega_kernel6Params.kd
    .uniform_work_group_size: 1
    .uses_dynamic_stack: false
    .vgpr_count:     256
    .vgpr_spill_count: 0
    .wavefront_size: 64
